# shared-LDS attention: Q fragments go straight to registers (no LDS round trip, no Q barrier); row and context DMAs issued at the pass top right after the Q loads
# baseline (speedup 1.0000x reference)
.LBB0_456:
	s_ashr_i32 s58, s4, 4
	s_lshl_b32 s0, s4, 2
	s_mul_hi_i32 s73, s58, 0x1100
	s_mul_i32 s74, s58, 0x1100
	s_and_b32 s5, s0, 60
	v_mov_b32_e32 v3, s73
	v_or_b32_e32 v2, s74, v216
	s_lshl_b32 s36, s5, 6
	v_lshl_add_u64 v[4:5], v[2:3], 0, s[36:37]
	v_lshlrev_b64 v[4:5], 10, v[4:5]
	v_lshl_add_u64 v[12:13], v[218:219], 0, v[4:5]
	s_mov_b32 s55, s37
	s_or_b32 s54, s36, 64
	global_load_dwordx4 v[4:7], v[12:13], off
	global_load_dwordx4 v[8:11], v[12:13], off offset:64
	v_lshl_add_u64 v[12:13], v[2:3], 0, s[54:55]
	v_lshlrev_b64 v[12:13], 10, v[12:13]
	v_lshl_add_u64 v[20:21], v[218:219], 0, v[12:13]
	global_load_dwordx4 v[12:15], v[20:21], off
	global_load_dwordx4 v[16:19], v[20:21], off offset:64
	s_mov_b32 s51, s37
	s_or_b32 s50, s36, 0x80
	v_lshl_add_u64 v[20:21], v[2:3], 0, s[50:51]
	v_lshlrev_b64 v[20:21], 10, v[20:21]
	v_lshl_add_u64 v[24:25], v[218:219], 0, v[20:21]
	global_load_dwordx4 v[20:23], v[24:25], off
	s_nop 0
	global_load_dwordx4 v[24:27], v[24:25], off offset:64
	v_sub_u32_e64 v1, s5, 1 clamp
	s_or_b32 s56, s36, 0xc0
	s_mov_b32 s57, s37
	v_readfirstlane_b32 s0, v1
	v_lshl_add_u64 v[2:3], v[2:3], 0, s[56:57]
	v_lshlrev_b64 v[2:3], 10, v[2:3]
	v_lshl_add_u64 v[2:3], v[218:219], 0, v[2:3]
	s_max_u32 s75, s5, 4
	s_min_u32 s0, s0, 56
	s_sub_i32 s83, s0, s75
	s_mul_i32 s0, s58, 0x220000
	s_or_b32 s7, s0, s72
	s_lshl_b32 s0, s58, 3
	s_add_i32 s76, s83, 12
	s_or_b32 s82, s0, s64
	s_add_i32 s80, s83, 19
	s_cmp_lt_i32 s83, -11
	s_mov_b64 s[0:1], -1
	s_waitcnt vmcnt(5)
	v_mov_b32_e32 v132, v4
	v_mov_b32_e32 v133, v5
	v_mov_b32_e32 v134, v6
	v_mov_b32_e32 v135, v7
	s_waitcnt vmcnt(4)
	v_mov_b32_e32 v136, v8
	v_mov_b32_e32 v137, v9
	v_mov_b32_e32 v138, v10
	v_mov_b32_e32 v139, v11
	v_lshlrev_b32_e32 v1, 16, v4
	v_and_b32_e32 v4, 0xffff0000, v4
	v_lshlrev_b32_e32 v28, 16, v8
	v_and_b32_e32 v8, 0xffff0000, v8
	v_lshlrev_b32_e32 v29, 16, v5
	v_and_b32_e32 v5, 0xffff0000, v5
	v_lshlrev_b32_e32 v30, 16, v9
	v_and_b32_e32 v9, 0xffff0000, v9
	v_lshlrev_b32_e32 v31, 16, v6
	v_and_b32_e32 v6, 0xffff0000, v6
	v_lshlrev_b32_e32 v32, 16, v10
	v_and_b32_e32 v10, 0xffff0000, v10
	v_lshlrev_b32_e32 v33, 16, v7
	v_and_b32_e32 v7, 0xffff0000, v7
	v_lshlrev_b32_e32 v34, 16, v11
	v_and_b32_e32 v11, 0xffff0000, v11
	v_mul_f32_e32 v4, v4, v4
	v_mul_f32_e32 v8, v8, v8
	v_mul_f32_e32 v5, v5, v5
	v_mul_f32_e32 v9, v9, v9
	v_mul_f32_e32 v6, v6, v6
	v_mul_f32_e32 v10, v10, v10
	v_mul_f32_e32 v7, v7, v7
	v_mul_f32_e32 v11, v11, v11
	s_waitcnt vmcnt(3)
	v_mov_b32_e32 v140, v12
	v_mov_b32_e32 v141, v13
	v_mov_b32_e32 v142, v14
	v_mov_b32_e32 v143, v15
	s_waitcnt vmcnt(2)
	v_mov_b32_e32 v144, v16
	v_mov_b32_e32 v145, v17
	v_mov_b32_e32 v146, v18
	v_mov_b32_e32 v147, v19
	v_fmac_f32_e32 v4, v1, v1
	v_fmac_f32_e32 v8, v28, v28
	v_fmac_f32_e32 v5, v29, v29
	v_fmac_f32_e32 v9, v30, v30
	v_fmac_f32_e32 v6, v31, v31
	v_fmac_f32_e32 v10, v32, v32
	v_fmac_f32_e32 v7, v33, v33
	v_fmac_f32_e32 v11, v34, v34
	v_add_f32_e32 v4, v4, v8
	v_add_f32_e32 v5, v5, v9
	v_add_f32_e32 v6, v6, v10
	v_add_f32_e32 v7, v7, v11
	global_load_dwordx4 v[8:11], v[2:3], off
	global_load_dwordx4 v[28:31], v[2:3], off offset:64
	v_bfe_u32 v164, v226, 2, 3
	v_lshrrev_b32_e32 v165, 5, v226
	v_lshl_add_u32 v164, v164, 3, v165
	v_and_b32_e32 v166, 3, v226
	v_lshlrev_b32_e32 v166, 4, v166
	v_lshl_add_u32 v241, v164, 10, v166
	v_bfe_u32 v164, v226, 2, 2
	v_lshrrev_b32_e32 v165, 4, v226
	v_lshl_add_u32 v164, v164, 3, v165
	v_mul_u32_u24_e32 v164, 0x2200, v164
	v_add_u32_e32 v255, v164, v166
	v_readfirstlane_b32 s21, v231
	s_nop 3
	s_sub_u32 s21, s21, 0x8000
	s_lshr_b32 s84, s21, 13
	s_lshl_b32 s94, s84, 10
	s_mul_i32 s22, s58, 0x220000
	s_or_b32 s22, s22, s72
	s_lshl_b32 s22, s22, 1
	s_lshr_b32 s20, s84, 2
	s_lshl_b32 s20, s20, 12
	s_and_b32 s21, s84, 1
	s_lshl_b32 s21, s21, 11
	s_add_u32 s20, s20, s21
	s_bfe_u32 s21, s84, 0x10001
	s_lshl_b32 s21, s21, 6
	s_add_u32 s20, s20, s21
	s_add_u32 s61, s20, s22
	s_lshl_b32 s22, s58, 3
	s_or_b32 s22, s22, s64
	s_mul_i32 s22, s22, 0x88000
	s_lshr_b32 s20, s84, 2
	s_mul_i32 s20, s20, 0x44000
	s_bfe_u32 s21, s84, 0x10001
	s_mul_i32 s21, s21, 0x8800
	s_add_u32 s20, s20, s21
	s_and_b32 s21, s84, 1
	s_lshl_b32 s21, s21, 6
	s_add_u32 s20, s20, s21
	s_add_u32 s62, s20, s22
	s_lshr_b32 s20, s5, 2
	s_max_u32 s87, s5, 4
	s_sub_u32 s87, s87, 4
	s_and_b32 s86, s20, 1
	s_lshl_b32 s22, s20, 2
	s_sub_i32 s22, s22, 8
	s_max_i32 s22, s22, 0
	s_sub_i32 s22, s87, s22
	s_cmp_eq_u32 s86, 1
	s_cselect_b32 s60, s22, 0
	s_sub_i32 s93, s87, s60
	s_and_b32 s20, s20, 14
	s_cmp_eq_u32 s20, 0
	s_cselect_b32 s22, 11, 15
	s_cmp_eq_u32 s20, 14
	s_cselect_b32 s88, 12, s22
	s_mov_b32 s42, s26
	s_mov_b32 s43, s27
	s_add_u32 s20, s93, 0
	s_mov_b32 s87, 0x18000
	s_lshl_b32 s21, s20, 16
	s_add_u32 s21, s21, s61
	s_lshl_b32 s22, s20, 7
	s_add_u32 s22, s22, s62
	s_add_u32 m0, s87, s94
	s_add_u32 s84, s87, s94
	s_add_u32 s84, s84, 0x2000
	buffer_load_dwordx4 v241, s[24:27], s21 offen lds
	s_mov_b32 m0, s84
	s_nop 0
	buffer_load_dwordx4 v255, s[40:43], s22 offen lds
	s_add_u32 s20, s93, 1
	s_mov_b32 s87, 0x1c000
	s_lshl_b32 s21, s20, 16
	s_add_u32 s21, s21, s61
	s_lshl_b32 s22, s20, 7
	s_add_u32 s22, s22, s62
	s_add_u32 m0, s87, s94
	s_add_u32 s84, s87, s94
	s_add_u32 s84, s84, 0x2000
	buffer_load_dwordx4 v241, s[24:27], s21 offen lds
	s_mov_b32 m0, s84
	s_nop 0
	buffer_load_dwordx4 v255, s[40:43], s22 offen lds
	s_add_u32 s20, s93, 2
	s_mov_b32 s87, 0x20010
	s_lshl_b32 s21, s20, 16
	s_add_u32 s21, s21, s61
	s_lshl_b32 s22, s20, 7
	s_add_u32 s22, s22, s62
	s_add_u32 m0, s87, s94
	s_add_u32 s84, s87, s94
	s_add_u32 s84, s84, 0x2000
	buffer_load_dwordx4 v241, s[24:27], s21 offen lds
	s_mov_b32 m0, s84
	s_nop 0
	buffer_load_dwordx4 v255, s[40:43], s22 offen lds
	s_mov_b32 s20, 64
	s_mov_b32 s87, 0x8000
	s_lshl_b32 s21, s20, 16
	s_add_u32 s21, s21, s61
	s_lshl_b32 s22, s20, 7
	s_add_u32 s22, s22, s62
	s_add_u32 m0, s87, s94
	s_add_u32 s84, s87, s94
	s_add_u32 s84, s84, 0x2000
	buffer_load_dwordx4 v241, s[24:27], s21 offen lds
	s_mov_b32 m0, s84
	s_nop 0
	buffer_load_dwordx4 v255, s[40:43], s22 offen lds
	s_mov_b32 s20, 65
	s_mov_b32 s87, 0xc000
	s_lshl_b32 s21, s20, 16
	s_add_u32 s21, s21, s61
	s_lshl_b32 s22, s20, 7
	s_add_u32 s22, s22, s62
	s_add_u32 m0, s87, s94
	s_add_u32 s84, s87, s94
	s_add_u32 s84, s84, 0x2000
	buffer_load_dwordx4 v241, s[24:27], s21 offen lds
	s_mov_b32 m0, s84
	s_nop 0
	buffer_load_dwordx4 v255, s[40:43], s22 offen lds
	s_mov_b32 s20, 66
	s_mov_b32 s87, 0x10000
	s_lshl_b32 s21, s20, 16
	s_add_u32 s21, s21, s61
	s_lshl_b32 s22, s20, 7
	s_add_u32 s22, s22, s62
	s_add_u32 m0, s87, s94
	s_add_u32 s84, s87, s94
	s_add_u32 s84, s84, 0x2000
	buffer_load_dwordx4 v241, s[24:27], s21 offen lds
	s_mov_b32 m0, s84
	s_nop 0
	buffer_load_dwordx4 v255, s[40:43], s22 offen lds
	s_mov_b32 s20, 67
	s_mov_b32 s87, 0x14000
	s_lshl_b32 s21, s20, 16
	s_add_u32 s21, s21, s61
	s_lshl_b32 s22, s20, 7
	s_add_u32 s22, s22, s62
	s_add_u32 m0, s87, s94
	s_add_u32 s84, s87, s94
	s_add_u32 s84, s84, 0x2000
	buffer_load_dwordx4 v241, s[24:27], s21 offen lds
	s_mov_b32 m0, s84
	s_nop 0
	buffer_load_dwordx4 v255, s[40:43], s22 offen lds
	v_lshlrev_b32_e32 v35, 16, v12
	v_and_b32_e32 v12, 0xffff0000, v12
	v_lshlrev_b32_e32 v36, 16, v16
	v_and_b32_e32 v16, 0xffff0000, v16
	v_mul_f32_e32 v1, v12, v12
	v_mul_f32_e32 v12, v16, v16
	v_lshlrev_b32_e32 v37, 16, v13
	v_and_b32_e32 v13, 0xffff0000, v13
	v_lshlrev_b32_e32 v38, 16, v17
	v_and_b32_e32 v17, 0xffff0000, v17
	v_fmac_f32_e32 v1, v35, v35
	v_fmac_f32_e32 v12, v36, v36
	v_add_f32_e32 v4, v4, v5
	v_mul_f32_e32 v13, v13, v13
	v_add_f32_e32 v5, v1, v12
	v_add_f32_e32 v1, v6, v4
	v_mul_f32_e32 v6, v17, v17
	v_fmac_f32_e32 v13, v37, v37
	v_fmac_f32_e32 v6, v38, v38
	v_add_f32_e32 v2, v13, v6
	v_add_f32_e32 v2, v5, v2
	v_and_b32_e32 v5, 0xffff0000, v14
	v_add_f32_e32 v1, v7, v1
	v_lshlrev_b32_e32 v3, 16, v14
	v_and_b32_e32 v7, 0xffff0000, v18
	v_mul_f32_e32 v5, v5, v5
	v_lshlrev_b32_e32 v6, 16, v18
	v_fmac_f32_e32 v5, v3, v3
	v_mul_f32_e32 v3, v7, v7
	v_fmac_f32_e32 v3, v6, v6
	v_add_f32_e32 v3, v5, v3
	v_and_b32_e32 v5, 0xffff0000, v15
	v_add_f32_e32 v2, v3, v2
	v_lshlrev_b32_e32 v3, 16, v15
	v_and_b32_e32 v7, 0xffff0000, v19
	v_mul_f32_e32 v5, v5, v5
	v_lshlrev_b32_e32 v6, 16, v19
	v_fmac_f32_e32 v5, v3, v3
	v_mul_f32_e32 v3, v7, v7
	v_fmac_f32_e32 v3, v6, v6
	s_waitcnt vmcnt(17)
	v_and_b32_e32 v6, 0xffff0000, v20
	v_add_f32_e32 v3, v5, v3
	v_lshlrev_b32_e32 v5, 16, v20
	s_waitcnt vmcnt(16)
	v_and_b32_e32 v12, 0xffff0000, v24
	v_mul_f32_e32 v6, v6, v6
	v_lshlrev_b32_e32 v7, 16, v24
	v_fmac_f32_e32 v6, v5, v5
	v_mul_f32_e32 v5, v12, v12
	v_fmac_f32_e32 v5, v7, v7
	v_and_b32_e32 v7, 0xffff0000, v21
	v_add_f32_e32 v5, v6, v5
	v_lshlrev_b32_e32 v6, 16, v21
	v_and_b32_e32 v13, 0xffff0000, v25
	v_mul_f32_e32 v7, v7, v7
	v_lshlrev_b32_e32 v12, 16, v25
	v_fmac_f32_e32 v7, v6, v6
	v_mul_f32_e32 v6, v13, v13
	v_fmac_f32_e32 v6, v12, v12
	v_add_f32_e32 v6, v7, v6
	v_and_b32_e32 v7, 0xffff0000, v22
	v_add_f32_e32 v5, v5, v6
	v_lshlrev_b32_e32 v6, 16, v22
	v_and_b32_e32 v13, 0xffff0000, v26
	v_mul_f32_e32 v7, v7, v7
	v_lshlrev_b32_e32 v12, 16, v26
	v_fmac_f32_e32 v7, v6, v6
	v_mul_f32_e32 v6, v13, v13
	v_fmac_f32_e32 v6, v12, v12
	v_add_f32_e32 v6, v7, v6
	v_and_b32_e32 v7, 0xffff0000, v23
	v_add_f32_e32 v5, v6, v5
	v_lshlrev_b32_e32 v6, 16, v23
	v_and_b32_e32 v13, 0xffff0000, v27
	v_mul_f32_e32 v7, v7, v7
	v_lshlrev_b32_e32 v12, 16, v27
	v_fmac_f32_e32 v7, v6, v6
	v_mul_f32_e32 v6, v13, v13
	v_fmac_f32_e32 v6, v12, v12
	v_mov_b32_e32 v148, v20
	v_mov_b32_e32 v149, v21
	v_mov_b32_e32 v150, v22
	v_mov_b32_e32 v151, v23
	v_mov_b32_e32 v152, v24
	v_mov_b32_e32 v153, v25
	v_mov_b32_e32 v154, v26
	v_mov_b32_e32 v155, v27
	v_add_f32_e32 v6, v7, v6
	s_waitcnt vmcnt(15)
	v_mov_b32_e32 v156, v8
	v_mov_b32_e32 v157, v9
	v_mov_b32_e32 v158, v10
	v_mov_b32_e32 v159, v11
	s_waitcnt vmcnt(14)
	v_mov_b32_e32 v160, v28
	v_mov_b32_e32 v161, v29
	v_mov_b32_e32 v162, v30
	v_mov_b32_e32 v163, v31
	v_lshlrev_b32_e32 v7, 16, v8
	v_and_b32_e32 v8, 0xffff0000, v8
	v_and_b32_e32 v13, 0xffff0000, v28
	v_mul_f32_e32 v8, v8, v8
	v_lshlrev_b32_e32 v12, 16, v28
	v_fmac_f32_e32 v8, v7, v7
	v_mul_f32_e32 v7, v13, v13
	v_fmac_f32_e32 v7, v12, v12
	v_add_f32_e32 v7, v8, v7
	v_lshlrev_b32_e32 v8, 16, v9
	v_and_b32_e32 v9, 0xffff0000, v9
	v_and_b32_e32 v13, 0xffff0000, v29
	v_mul_f32_e32 v9, v9, v9
	v_lshlrev_b32_e32 v12, 16, v29
	v_fmac_f32_e32 v9, v8, v8
	v_mul_f32_e32 v8, v13, v13
	v_fmac_f32_e32 v8, v12, v12
	v_add_f32_e32 v8, v9, v8
	v_and_b32_e32 v9, 0xffff0000, v10
	v_add_f32_e32 v7, v7, v8
	v_lshlrev_b32_e32 v8, 16, v10
	v_and_b32_e32 v12, 0xffff0000, v30
	v_mul_f32_e32 v9, v9, v9
	v_lshlrev_b32_e32 v10, 16, v30
	v_fmac_f32_e32 v9, v8, v8
	v_mul_f32_e32 v8, v12, v12
	v_fmac_f32_e32 v8, v10, v10
	v_add_f32_e32 v8, v9, v8
	v_and_b32_e32 v9, 0xffff0000, v11
	v_add_f32_e32 v7, v8, v7
	v_lshlrev_b32_e32 v8, 16, v11
	v_and_b32_e32 v11, 0xffff0000, v31
	v_mul_f32_e32 v9, v9, v9
	v_lshlrev_b32_e32 v10, 16, v31
	v_fmac_f32_e32 v9, v8, v8
	v_mul_f32_e32 v8, v11, v11
	v_fmac_f32_e32 v8, v10, v10
	v_add_f32_e32 v8, v9, v8
	v_add_f32_e32 v2, v3, v2
	v_add_f32_e32 v5, v6, v5
	v_add_f32_e32 v7, v8, v7
	v_mov_b32_e32 v4, v1
	v_mov_b32_e32 v3, v2
	v_mov_b32_e32 v6, v5
	v_mov_b32_e32 v8, v7
	v_permlane16_swap_b32_e32 v1, v4
	v_permlane16_swap_b32_e32 v2, v3
	v_permlane16_swap_b32_e32 v5, v6
	v_permlane16_swap_b32_e32 v7, v8
	v_add_f32_e32 v1, v1, v4
	v_add_f32_e32 v2, v2, v3
	v_add_f32_e32 v5, v5, v6
	v_add_f32_e32 v7, v7, v8
	v_mov_b32_e32 v4, v1
	v_mov_b32_e32 v3, v2
	v_mov_b32_e32 v6, v5
	v_mov_b32_e32 v8, v7
	v_sub_u32_e64 v9, s5, 4 clamp
	v_permlane32_swap_b32_e32 v1, v4
	v_permlane32_swap_b32_e32 v2, v3
	v_permlane32_swap_b32_e32 v5, v6
	v_permlane32_swap_b32_e32 v7, v8
	v_readfirstlane_b32 s77, v9
	s_cbranch_scc0 .LBB0_458
	s_min_i32 s0, s80, 0
	s_sub_i32 s0, s0, s76
	s_lshl_b32 s0, s0, 5
	s_add_i32 s6, s0, 0x1000
	s_cbranch_execnz .LBB0_460
	s_branch .LBB0_459

.LBB0_465:
	v_add_f32_e32 v1, v1, v4
	v_mul_f32_e32 v4, 0x4f800000, v1
	v_cmp_gt_f32_e32 vcc, s70, v1
	v_add_f32_e32 v2, v2, v3
	v_mul_f32_e32 v3, 0x4f800000, v2
	v_cndmask_b32_e32 v1, v1, v4, vcc
	v_sqrt_f32_e32 v4, v1
	s_mul_i32 s82, s82, 0x88000
	s_lshl_b32 s81, s7, 1
	s_mov_b32 s42, s26
	v_add_u32_e32 v9, -1, v4
	v_fma_f32 v10, -v9, v4, v1
	v_cmp_ge_f32_e64 s[0:1], 0, v10
	v_add_u32_e32 v10, 1, v4
	s_mov_b32 s43, s27
	v_cndmask_b32_e64 v9, v4, v9, s[0:1]
	v_fma_f32 v4, -v10, v4, v1
	v_cmp_lt_f32_e64 s[0:1], 0, v4
	s_or_b32 s20, s5, 1
	s_and_b32 s4, s4, 15
	v_cndmask_b32_e64 v4, v9, v10, s[0:1]
	v_mul_f32_e32 v9, 0x37800000, v4
	v_cndmask_b32_e32 v4, v4, v9, vcc
	v_cmp_gt_f32_e32 vcc, s70, v2
	v_cmp_class_f32_e64 s[0:1], v1, v237
	s_lshl_b32 s4, s4, 10
	v_cndmask_b32_e32 v2, v2, v3, vcc
	v_sqrt_f32_e32 v3, v2
	v_cndmask_b32_e64 v1, v4, v1, s[0:1]
	s_waitcnt lgkmcnt(8)
	v_fma_f32 v1, v227, v1, v228
	v_mov_b32_e32 v224, 0
	v_add_u32_e32 v4, -1, v3
	v_fma_f32 v9, -v4, v3, v2
	v_cmp_ge_f32_e64 s[0:1], 0, v9
	v_add_u32_e32 v9, 1, v3
	s_mov_b32 s92, 0
	v_cndmask_b32_e64 v4, v3, v4, s[0:1]
	v_fma_f32 v3, -v9, v3, v2
	v_cmp_lt_f32_e64 s[0:1], 0, v3
	s_add_i32 s83, s83, 20
	s_add_i32 s84, s75, 4
	v_cndmask_b32_e64 v3, v4, v9, s[0:1]
	v_mul_f32_e32 v4, 0x37800000, v3
	v_cndmask_b32_e32 v3, v3, v4, vcc
	v_add_f32_e32 v4, v5, v6
	v_mul_f32_e32 v5, 0x4f800000, v4
	v_cmp_gt_f32_e32 vcc, s70, v4
	v_cmp_class_f32_e64 s[0:1], v2, v237
	v_mov_b32_e32 v225, v224
	v_cndmask_b32_e32 v4, v4, v5, vcc
	v_sqrt_f32_e32 v5, v4
	v_cndmask_b32_e64 v2, v3, v2, s[0:1]
	v_fma_f32 v2, v227, v2, v228
	v_max3_f32 v1, v1, 0, v2
	v_add_u32_e32 v2, -1, v5
	v_fma_f32 v3, -v2, v5, v4
	v_cmp_ge_f32_e64 s[0:1], 0, v3
	v_add_u32_e32 v3, 1, v5
	v_mov_b32_e32 v222, v224
	v_cndmask_b32_e64 v2, v5, v2, s[0:1]
	v_fma_f32 v5, -v3, v5, v4
	v_cmp_lt_f32_e64 s[0:1], 0, v5
	v_mov_b32_e32 v223, v224
	s_nop 0
	v_cndmask_b32_e64 v2, v2, v3, s[0:1]
	v_mul_f32_e32 v3, 0x37800000, v2
	s_lshl_b32 s0, s8, 1
	v_cndmask_b32_e32 v2, v2, v3, vcc
	v_cmp_class_f32_e32 vcc, v4, v237
	v_add_f32_e32 v3, v7, v8
	s_add_i32 s0, s0, s82
	v_cndmask_b32_e32 v2, v2, v4, vcc
	v_mul_f32_e32 v4, 0x4f800000, v3
	v_cmp_gt_f32_e32 vcc, s70, v3
	s_add_i32 s7, s0, 0x44000
	s_add_i32 s1, s0, 0x4c800
	v_cndmask_b32_e32 v3, v3, v4, vcc
	s_add_i32 s9, s0, 0x8800
	v_sqrt_f32_e32 v52, v3
	v_fma_f32 v2, v227, v2, v228
	v_add_u32_e32 v53, -1, v52
	v_fma_f32 v54, -v53, v52, v3
	v_cmp_ge_f32_e64 s[0:1], 0, v54
	v_add_u32_e32 v54, 1, v52
	s_nop 0
	v_cndmask_b32_e64 v53, v52, v53, s[0:1]
	v_fma_f32 v52, -v54, v52, v3
	v_cmp_lt_f32_e64 s[0:1], 0, v52
	s_nop 1
	v_cndmask_b32_e64 v52, v53, v54, s[0:1]
	v_mul_f32_e32 v53, 0x37800000, v52
	v_cndmask_b32_e32 v52, v52, v53, vcc
	v_cmp_class_f32_e32 vcc, v3, v237
	s_nop 1
	v_cndmask_b32_e32 v3, v52, v3, vcc
	v_fma_f32 v3, v227, v3, v228
	v_max3_f32 v239, v1, v2, v3
	v_add_u32_e32 v1, s59, v232
	v_sub_u32_e32 v1, v229, v1
	v_add_u32_e32 v2, 15, v1
	v_cmp_gt_u32_e64 s[0:1], 16, v2
	v_add_u32_e32 v2, 14, v1
	v_cmp_gt_u32_e64 s[6:7], 16, v2
	v_add_u32_e32 v2, 13, v1
	v_cmp_gt_u32_e64 s[8:9], 16, v2
	v_add_u32_e32 v2, 12, v1
	v_cmp_gt_u32_e64 s[10:11], 16, v2
	v_add_u32_e32 v2, 11, v1
	v_cmp_gt_u32_e64 s[12:13], 16, v2
	v_add_u32_e32 v2, 10, v1
	v_cmp_gt_u32_e64 s[14:15], 16, v2
	v_add_u32_e32 v2, 9, v1
	v_add_u32_e32 v1, 8, v1
	v_cmp_gt_u32_e64 s[18:19], 16, v1
	v_sub_u32_e64 v1, s20, 4 clamp
	v_cmp_gt_u32_e64 s[16:17], 16, v2
	v_readfirstlane_b32 s20, v1
	s_min_u32 s85, s20, 56
	s_or_b32 s20, s5, 2
	v_sub_u32_e64 v1, s20, 4 clamp
	s_or_b32 s5, s5, 3
	v_readfirstlane_b32 s20, v1
	v_sub_u32_e64 v1, s5, 4 clamp
	s_min_u32 s87, s20, 56
	v_readfirstlane_b32 s5, v1
	s_min_u32 s89, s5, 56
	s_lshl_b32 s5, s75, 8
	s_lshl_b32 s20, s59, 2
	s_or_b32 s5, s5, s20
	v_lshrrev_b32_e32 v85, 4, v226
	v_and_b32_e32 v86, 15, v226
	v_lshlrev_b32_e32 v233, 9, v85
	v_lshl_add_u32 v233, v86, 4, v233
	v_lshlrev_b32_e32 v234, 4, v226
	s_lshl_b32 s97, s59, 3
	s_lshl_b32 s90, s59, 5
	s_add_u32 s90, s90, 0x2000
	s_sub_i32 s4, s5, s4
	v_add_u32_e32 v240, s4, v236
	ds_read2_b32 v[204:205], v240 offset0:192 offset1:193
	ds_read2_b32 v[206:207], v240 offset0:194 offset1:195
	ds_read2_b32 v[208:209], v240 offset0:196 offset1:197
	ds_read2_b32 v[210:211], v240 offset0:198 offset1:199
	ds_read2_b32 v[80:81], v240 offset0:128 offset1:129
	ds_read2_b32 v[82:83], v240 offset0:130 offset1:131
	ds_read2_b32 v[84:85], v240 offset0:132 offset1:133
	ds_read2_b32 v[86:87], v240 offset0:134 offset1:135
	ds_read2_b32 v[180:181], v240 offset0:64 offset1:65
	ds_read2_b32 v[182:183], v240 offset0:66 offset1:67
	ds_read2_b32 v[184:185], v240 offset0:68 offset1:69
	ds_read2_b32 v[186:187], v240 offset0:70 offset1:71
	ds_read2_b32 v[212:213], v240 offset0:0 offset1:1
	ds_read2_b32 v[214:215], v240 offset0:2 offset1:3
	ds_read2_b32 v[242:243], v240 offset0:4 offset1:5
	ds_read2_b32 v[244:245], v240 offset0:6 offset1:7
	v_xor_b32_e32 v76, 0x80000000, v239
	v_xor_b32_e32 v77, 0x80000000, v239
	v_xor_b32_e32 v78, 0x80000000, v239
	v_xor_b32_e32 v79, 0x80000000, v239
	v_mov_b32_e32 v96, 0
	v_mov_b32_e32 v97, 0
	v_mov_b32_e32 v98, 0
	v_mov_b32_e32 v99, 0
	v_mov_b32_e32 v88, 0
	v_mov_b32_e32 v89, 0
	v_mov_b32_e32 v90, 0
	v_mov_b32_e32 v91, 0
	v_mov_b32_e32 v72, 0
	v_mov_b32_e32 v73, 0
	v_mov_b32_e32 v74, 0
	v_mov_b32_e32 v75, 0
	v_mov_b32_e32 v68, 0
	v_mov_b32_e32 v69, 0
	v_mov_b32_e32 v70, 0
	v_mov_b32_e32 v71, 0
	v_mov_b32_e32 v222, 0
	v_mov_b32_e32 v64, 0
	v_mov_b32_e32 v65, 0
	v_mov_b32_e32 v66, 0
	v_mov_b32_e32 v67, 0
	v_mov_b32_e32 v60, 0
	v_mov_b32_e32 v61, 0
	v_mov_b32_e32 v62, 0
	v_mov_b32_e32 v63, 0
	v_mov_b32_e32 v56, 0
	v_mov_b32_e32 v57, 0
	v_mov_b32_e32 v58, 0
	v_mov_b32_e32 v59, 0
	v_mov_b32_e32 v52, 0
	v_mov_b32_e32 v53, 0
	v_mov_b32_e32 v54, 0
	v_mov_b32_e32 v55, 0
	v_mov_b32_e32 v223, 0
	v_mov_b32_e32 v128, 0
	v_mov_b32_e32 v129, 0
	v_mov_b32_e32 v130, 0
	v_mov_b32_e32 v131, 0
	v_mov_b32_e32 v124, 0
	v_mov_b32_e32 v125, 0
	v_mov_b32_e32 v126, 0
	v_mov_b32_e32 v127, 0
	v_mov_b32_e32 v120, 0
	v_mov_b32_e32 v121, 0
	v_mov_b32_e32 v122, 0
	v_mov_b32_e32 v123, 0
	v_mov_b32_e32 v116, 0
	v_mov_b32_e32 v117, 0
	v_mov_b32_e32 v118, 0
	v_mov_b32_e32 v119, 0
	v_mov_b32_e32 v224, 0
	v_mov_b32_e32 v112, 0
	v_mov_b32_e32 v113, 0
	v_mov_b32_e32 v114, 0
	v_mov_b32_e32 v115, 0
	v_mov_b32_e32 v108, 0
	v_mov_b32_e32 v109, 0
	v_mov_b32_e32 v110, 0
	v_mov_b32_e32 v111, 0
	v_mov_b32_e32 v104, 0
	v_mov_b32_e32 v105, 0
	v_mov_b32_e32 v106, 0
	v_mov_b32_e32 v107, 0
	v_mov_b32_e32 v100, 0
	v_mov_b32_e32 v101, 0
	v_mov_b32_e32 v102, 0
	v_mov_b32_e32 v103, 0
	v_mov_b32_e32 v225, 0
	s_waitcnt lgkmcnt(0)
	v_sub_f32_e32 v204, v204, v239
	v_sub_f32_e32 v205, v205, v239
	v_sub_f32_e32 v206, v206, v239
	v_sub_f32_e32 v207, v207, v239
	v_sub_f32_e32 v208, v208, v239
	v_sub_f32_e32 v209, v209, v239
	v_sub_f32_e32 v210, v210, v239
	v_sub_f32_e32 v211, v211, v239
	v_cndmask_b32_e64 v204, v238, v204, s[0:1]
	v_cndmask_b32_e64 v205, v238, v205, s[6:7]
	v_cndmask_b32_e64 v206, v238, v206, s[8:9]
	v_cndmask_b32_e64 v207, v238, v207, s[10:11]
	v_cndmask_b32_e64 v208, v238, v208, s[12:13]
	v_cndmask_b32_e64 v209, v238, v209, s[14:15]
	v_cndmask_b32_e64 v210, v238, v210, s[16:17]
	v_cndmask_b32_e64 v211, v238, v211, s[18:19]
	v_sub_f32_e32 v80, v80, v239
	v_sub_f32_e32 v81, v81, v239
	v_sub_f32_e32 v82, v82, v239
	v_sub_f32_e32 v83, v83, v239
	v_sub_f32_e32 v84, v84, v239
	v_sub_f32_e32 v85, v85, v239
	v_sub_f32_e32 v86, v86, v239
	v_sub_f32_e32 v87, v87, v239
	v_cndmask_b32_e64 v80, v238, v80, s[0:1]
	v_cndmask_b32_e64 v81, v238, v81, s[6:7]
	v_cndmask_b32_e64 v82, v238, v82, s[8:9]
	v_cndmask_b32_e64 v83, v238, v83, s[10:11]
	v_cndmask_b32_e64 v84, v238, v84, s[12:13]
	v_cndmask_b32_e64 v85, v238, v85, s[14:15]
	v_cndmask_b32_e64 v86, v238, v86, s[16:17]
	v_cndmask_b32_e64 v87, v238, v87, s[18:19]
	v_sub_f32_e32 v180, v180, v239
	v_sub_f32_e32 v181, v181, v239
	v_sub_f32_e32 v182, v182, v239
	v_sub_f32_e32 v183, v183, v239
	v_sub_f32_e32 v184, v184, v239
	v_sub_f32_e32 v185, v185, v239
	v_sub_f32_e32 v186, v186, v239
	v_sub_f32_e32 v187, v187, v239
	v_cndmask_b32_e64 v180, v238, v180, s[0:1]
	v_cndmask_b32_e64 v181, v238, v181, s[6:7]
	v_cndmask_b32_e64 v182, v238, v182, s[8:9]
	v_cndmask_b32_e64 v183, v238, v183, s[10:11]
	v_cndmask_b32_e64 v184, v238, v184, s[12:13]
	v_cndmask_b32_e64 v185, v238, v185, s[14:15]
	v_cndmask_b32_e64 v186, v238, v186, s[16:17]
	v_cndmask_b32_e64 v187, v238, v187, s[18:19]
	v_sub_f32_e32 v212, v212, v239
	v_sub_f32_e32 v213, v213, v239
	v_sub_f32_e32 v214, v214, v239
	v_sub_f32_e32 v215, v215, v239
	v_sub_f32_e32 v242, v242, v239
	v_sub_f32_e32 v243, v243, v239
	v_sub_f32_e32 v244, v244, v239
	v_sub_f32_e32 v245, v245, v239
	v_cndmask_b32_e64 v212, v238, v212, s[0:1]
	v_cndmask_b32_e64 v213, v238, v213, s[6:7]
	v_cndmask_b32_e64 v214, v238, v214, s[8:9]
	v_cndmask_b32_e64 v215, v238, v215, s[10:11]
	v_cndmask_b32_e64 v242, v238, v242, s[12:13]
	v_cndmask_b32_e64 v243, v238, v243, s[14:15]
	v_cndmask_b32_e64 v244, v238, v244, s[16:17]
	v_cndmask_b32_e64 v245, v238, v245, s[18:19]
	v_add_u32_e32 v240, 0x400, v240
	s_mov_b32 s92, -1
	s_mov_b32 s63, 2
	s_waitcnt vmcnt(0) lgkmcnt(0)
	s_barrier
	s_add_u32 s92, s92, 1
	s_add_u32 s63, s63, 1
	s_cmp_eq_u32 s63, 3
	s_cselect_b32 s63, 0, s63
	s_lshl_b32 s95, s63, 14
	s_lshr_b32 s20, s63, 1
	s_lshl_b32 s20, s20, 4
	s_add_u32 s95, s95, s20
	s_add_u32 s95, s95, 0x18000
	s_sub_i32 s21, s92, s60
	s_sub_i32 s22, s92, s76
	s_cmp_lt_i32 s21, 0
	s_cselect_b32 s22, s92, s22
	s_max_i32 s22, s22, 0
	s_min_i32 s22, s22, 7
	s_lshr_b32 s84, s22, 1
	s_lshl_b32 s84, s84, 14
	s_add_u32 s84, s84, 0x8000
	s_and_b32 s87, s22, 1
	s_lshl_b32 s20, s87, 8
	s_add_u32 s23, s84, s20
	s_lshl_b32 s20, s87, 10
	s_add_u32 s33, s84, s20
	s_add_u32 s33, s33, 0x2000
	s_cmp_ge_i32 s21, 0
	s_cselect_b32 s20, 1, 0
	s_cmp_lt_i32 s21, s76
	s_cselect_b32 s20, s20, 0
	s_cmp_lg_u32 s20, 0
	s_cbranch_scc0 .Latt_cs2
	s_add_u32 s23, s95, s97
	s_add_u32 s33, s95, s90
.Latt_cs2:
	v_add_u32_e32 v251, s23, v233
	v_add_u32_e32 v253, s33, v234
	ds_read_b128 v[176:179], v251 offset:0
	ds_read_b128 v[168:171], v251 offset:4096
	ds_read_b128 v[172:175], v251 offset:2048
	ds_read_b128 v[164:167], v251 offset:6144
	ds_read_b128 v[32:35], v253 offset:0
	ds_read_b128 v[28:31], v253 offset:2048
	ds_read_b128 v[24:27], v253 offset:4096
	ds_read_b128 v[20:23], v253 offset:6144
	s_mov_b32 s85, 0
	s_cmp_eq_u32 s60, 0
	s_cbranch_scc1 .Latt_went
	s_mov_b32 s85, 1
	s_mov_b32 s91, 4
	s_branch .Latt_CA
.Latt_went:
	s_mov_b32 s85, 0
	s_cmp_eq_u32 s76, 8
	s_cbranch_scc1 .Latt_n8
	s_waitcnt lgkmcnt(0)
	s_waitcnt vmcnt(2)
	s_barrier
	s_add_u32 s20, s92, 3
	s_cmp_ge_u32 s20, s88
	s_cbranch_scc1 .Latt_sk3
	s_add_u32 s20, s20, s93
	s_lshl_b32 s21, s20, 16
	s_add_u32 s21, s21, s61
	s_lshl_b32 s22, s20, 7
	s_add_u32 s22, s22, s62
	s_add_u32 m0, s95, s94
	s_add_u32 s84, s95, s94
	s_add_u32 s84, s84, 0x2000
	buffer_load_dwordx4 v241, s[24:27], s21 offen lds
	s_mov_b32 m0, s84
	s_nop 0
	buffer_load_dwordx4 v255, s[40:43], s22 offen lds
.Latt_sk3:
	s_add_u32 s92, s92, 1
	s_add_u32 s63, s63, 1
	s_cmp_eq_u32 s63, 3
	s_cselect_b32 s63, 0, s63
	s_lshl_b32 s95, s63, 14
	s_lshr_b32 s20, s63, 1
	s_lshl_b32 s20, s20, 4
	s_add_u32 s95, s95, s20
	s_add_u32 s95, s95, 0x18000
	s_sub_i32 s21, s92, s60
	s_sub_i32 s22, s92, s76
	s_cmp_lt_i32 s21, 0
	s_cselect_b32 s22, s92, s22
	s_max_i32 s22, s22, 0
	s_min_i32 s22, s22, 7
	s_lshr_b32 s84, s22, 1
	s_lshl_b32 s84, s84, 14
	s_add_u32 s84, s84, 0x8000
	s_and_b32 s87, s22, 1
	s_lshl_b32 s20, s87, 8
	s_add_u32 s23, s84, s20
	s_lshl_b32 s20, s87, 10
	s_add_u32 s33, s84, s20
	s_add_u32 s33, s33, 0x2000
	s_cmp_ge_i32 s21, 0
	s_cselect_b32 s20, 1, 0
	s_cmp_lt_i32 s21, s76
	s_cselect_b32 s20, s20, 0
	s_cmp_lg_u32 s20, 0
	s_cbranch_scc0 .Latt_cs4
	s_add_u32 s23, s95, s97
	s_add_u32 s33, s95, s90
.Latt_cs4:
	v_add_u32_e32 v251, s23, v233
	v_add_u32_e32 v253, s33, v234
	ds_read_b128 v[48:51], v251 offset:0
	ds_read_b128 v[40:43], v251 offset:4096
	ds_read_b128 v[44:47], v251 offset:2048
	ds_read_b128 v[36:39], v251 offset:6144
	ds_read_b128 v[16:19], v253 offset:0
	ds_read_b128 v[12:15], v253 offset:2048
	ds_read_b128 v[8:11], v253 offset:4096
	ds_read_b128 v[4:7], v253 offset:6144
	ds_read2_b32 v[212:213], v240 offset0:0 offset1:1
	ds_read2_b32 v[214:215], v240 offset0:2 offset1:3
	ds_read2_b32 v[242:243], v240 offset0:4 offset1:5
	ds_read2_b32 v[244:245], v240 offset0:6 offset1:7
	v_mfma_f32_16x16x32_bf16 v[188:191], v[176:179], v[132:135], v[204:207]
	v_mfma_f32_16x16x32_bf16 v[192:195], v[168:171], v[132:135], v[208:211]
	v_mfma_f32_16x16x32_bf16 v[188:191], v[172:175], v[136:139], v[188:191]
	v_mfma_f32_16x16x32_bf16 v[192:195], v[164:167], v[136:139], v[192:195]
	s_nop 6
	v_exp_f32_e32 v188, v188
	v_exp_f32_e32 v189, v189
	v_exp_f32_e32 v190, v190
	v_exp_f32_e32 v191, v191
	v_exp_f32_e32 v192, v192
	v_exp_f32_e32 v193, v193
	v_exp_f32_e32 v194, v194
	v_exp_f32_e32 v195, v195
	v_cvt_pk_bf16_f32 v246, v188, v189
	v_cvt_pk_bf16_f32 v247, v190, v191
	v_cvt_pk_bf16_f32 v248, v192, v193
	v_cvt_pk_bf16_f32 v249, v194, v195
	v_add_f32_e32 v188, v188, v189
	v_add_f32_e32 v190, v190, v191
	v_add_f32_e32 v192, v192, v193
	v_add_f32_e32 v194, v194, v195
	v_add_f32_e32 v188, v188, v190
	v_add_f32_e32 v192, v192, v194
	v_add_f32_e32 v188, v188, v192
	v_add_f32_e32 v222, v222, v188
	s_waitcnt lgkmcnt(0)
	v_sub_f32_e32 v212, v212, v239
	v_sub_f32_e32 v213, v213, v239
	v_sub_f32_e32 v214, v214, v239
	v_mfma_f32_16x16x32_bf16 v[96:99], v[32:35], v[246:249], v[96:99]
	v_sub_f32_e32 v215, v215, v239
	v_sub_f32_e32 v242, v242, v239
	v_sub_f32_e32 v243, v243, v239
	v_mfma_f32_16x16x32_bf16 v[88:91], v[28:31], v[246:249], v[88:91]
	v_sub_f32_e32 v244, v244, v239
	v_sub_f32_e32 v245, v245, v239
	v_cndmask_b32_e64 v212, v238, v212, s[0:1]
	v_mfma_f32_16x16x32_bf16 v[72:75], v[24:27], v[246:249], v[72:75]
	v_cndmask_b32_e64 v213, v238, v213, s[6:7]
	v_cndmask_b32_e64 v214, v238, v214, s[8:9]
	v_cndmask_b32_e64 v215, v238, v215, s[10:11]
	v_mfma_f32_16x16x32_bf16 v[68:71], v[20:23], v[246:249], v[68:71]
	v_cndmask_b32_e64 v242, v238, v242, s[12:13]
	v_cndmask_b32_e64 v243, v238, v243, s[14:15]
	v_cndmask_b32_e64 v244, v238, v244, s[16:17]
	v_cndmask_b32_e64 v245, v238, v245, s[18:19]
	v_add_u32_e32 v240, 0x100, v240
	s_waitcnt lgkmcnt(0)
	s_waitcnt vmcnt(2)
	s_barrier
	s_add_u32 s20, s92, 3
	s_cmp_ge_u32 s20, s88
	s_cbranch_scc1 .Latt_sk5
	s_add_u32 s20, s20, s93
	s_lshl_b32 s21, s20, 16
	s_add_u32 s21, s21, s61
	s_lshl_b32 s22, s20, 7
	s_add_u32 s22, s22, s62
	s_add_u32 m0, s95, s94
	s_add_u32 s84, s95, s94
	s_add_u32 s84, s84, 0x2000
	buffer_load_dwordx4 v241, s[24:27], s21 offen lds
	s_mov_b32 m0, s84
	s_nop 0
	buffer_load_dwordx4 v255, s[40:43], s22 offen lds

.Latt_cs6:
	v_add_u32_e32 v251, s23, v233
	v_add_u32_e32 v253, s33, v234
	ds_read_b128 v[176:179], v251 offset:0
	ds_read_b128 v[168:171], v251 offset:4096
	ds_read_b128 v[172:175], v251 offset:2048
	ds_read_b128 v[164:167], v251 offset:6144
	ds_read_b128 v[32:35], v253 offset:0
	ds_read_b128 v[28:31], v253 offset:2048
	ds_read_b128 v[24:27], v253 offset:4096
	ds_read_b128 v[20:23], v253 offset:6144
	ds_read2_b32 v[180:181], v240 offset0:0 offset1:1
	ds_read2_b32 v[182:183], v240 offset0:2 offset1:3
	ds_read2_b32 v[184:185], v240 offset0:4 offset1:5
	ds_read2_b32 v[186:187], v240 offset0:6 offset1:7
	v_mfma_f32_16x16x32_bf16 v[188:191], v[48:51], v[140:143], v[204:207]
	v_mfma_f32_16x16x32_bf16 v[192:195], v[40:43], v[140:143], v[208:211]
	v_mfma_f32_16x16x32_bf16 v[188:191], v[44:47], v[144:147], v[188:191]
	v_mfma_f32_16x16x32_bf16 v[192:195], v[36:39], v[144:147], v[192:195]
	v_mfma_f32_16x16x32_bf16 v[196:199], v[48:51], v[132:135], v[212:215]
	v_mfma_f32_16x16x32_bf16 v[200:203], v[40:43], v[132:135], v[242:245]
	v_mfma_f32_16x16x32_bf16 v[196:199], v[44:47], v[136:139], v[196:199]
	v_mfma_f32_16x16x32_bf16 v[200:203], v[36:39], v[136:139], v[200:203]
	s_nop 2
	v_exp_f32_e32 v188, v188
	v_exp_f32_e32 v189, v189
	v_exp_f32_e32 v190, v190
	v_exp_f32_e32 v191, v191
	v_exp_f32_e32 v192, v192
	v_exp_f32_e32 v193, v193
	v_exp_f32_e32 v194, v194
	v_exp_f32_e32 v195, v195
	v_cvt_pk_bf16_f32 v246, v188, v189
	v_cvt_pk_bf16_f32 v247, v190, v191
	v_cvt_pk_bf16_f32 v248, v192, v193
	v_cvt_pk_bf16_f32 v249, v194, v195
	v_add_f32_e32 v188, v188, v189
	v_add_f32_e32 v190, v190, v191
	v_add_f32_e32 v192, v192, v193
	v_add_f32_e32 v194, v194, v195
	v_add_f32_e32 v188, v188, v190
	v_add_f32_e32 v192, v192, v194
	v_add_f32_e32 v188, v188, v192
	v_add_f32_e32 v223, v223, v188
	v_exp_f32_e32 v196, v196
	v_exp_f32_e32 v197, v197
	v_exp_f32_e32 v198, v198
	v_exp_f32_e32 v199, v199
	v_mfma_f32_16x16x32_bf16 v[64:67], v[16:19], v[246:249], v[64:67]
	v_exp_f32_e32 v200, v200
	v_exp_f32_e32 v201, v201
	v_exp_f32_e32 v202, v202
	v_exp_f32_e32 v203, v203
	v_mfma_f32_16x16x32_bf16 v[60:63], v[12:15], v[246:249], v[60:63]
	v_cvt_pk_bf16_f32 v92, v196, v197
	v_cvt_pk_bf16_f32 v93, v198, v199
	v_cvt_pk_bf16_f32 v94, v200, v201
	v_cvt_pk_bf16_f32 v95, v202, v203
	v_mfma_f32_16x16x32_bf16 v[56:59], v[8:11], v[246:249], v[56:59]
	v_add_f32_e32 v196, v196, v197
	v_add_f32_e32 v198, v198, v199
	v_add_f32_e32 v200, v200, v201
	v_add_f32_e32 v202, v202, v203
	v_mfma_f32_16x16x32_bf16 v[52:55], v[4:7], v[246:249], v[52:55]
	v_add_f32_e32 v196, v196, v198
	v_add_f32_e32 v200, v200, v202
	v_add_f32_e32 v196, v196, v200
	v_add_f32_e32 v222, v222, v196
	s_waitcnt lgkmcnt(0)
	v_sub_f32_e32 v180, v180, v239
	v_sub_f32_e32 v181, v181, v239
	v_sub_f32_e32 v182, v182, v239
	v_mfma_f32_16x16x32_bf16 v[96:99], v[16:19], v[92:95], v[96:99]
	v_sub_f32_e32 v183, v183, v239
	v_sub_f32_e32 v184, v184, v239
	v_sub_f32_e32 v185, v185, v239
	v_mfma_f32_16x16x32_bf16 v[88:91], v[12:15], v[92:95], v[88:91]
	v_sub_f32_e32 v186, v186, v239
	v_sub_f32_e32 v187, v187, v239
	v_cndmask_b32_e64 v180, v238, v180, s[0:1]
	v_mfma_f32_16x16x32_bf16 v[72:75], v[8:11], v[92:95], v[72:75]
	v_cndmask_b32_e64 v181, v238, v181, s[6:7]
	v_cndmask_b32_e64 v182, v238, v182, s[8:9]
	v_cndmask_b32_e64 v183, v238, v183, s[10:11]
	v_mfma_f32_16x16x32_bf16 v[68:71], v[4:7], v[92:95], v[68:71]
	v_cndmask_b32_e64 v184, v238, v184, s[12:13]
	v_cndmask_b32_e64 v185, v238, v185, s[14:15]
	v_cndmask_b32_e64 v186, v238, v186, s[16:17]
	v_cndmask_b32_e64 v187, v238, v187, s[18:19]
	v_add_u32_e32 v240, 0x100, v240
	s_waitcnt lgkmcnt(0)
	s_waitcnt vmcnt(2)
	s_barrier
	s_add_u32 s20, s92, 3
	s_cmp_ge_u32 s20, s88
	s_cbranch_scc1 .Latt_sk7
	s_add_u32 s20, s20, s93
	s_lshl_b32 s21, s20, 16
	s_add_u32 s21, s21, s61
	s_lshl_b32 s22, s20, 7
	s_add_u32 s22, s22, s62
	s_add_u32 m0, s95, s94
	s_add_u32 s84, s95, s94
	s_add_u32 s84, s84, 0x2000
	buffer_load_dwordx4 v241, s[24:27], s21 offen lds
	s_mov_b32 m0, s84
	s_nop 0
	buffer_load_dwordx4 v255, s[40:43], s22 offen lds

.Latt_cs8:
	v_add_u32_e32 v251, s23, v233
	v_add_u32_e32 v253, s33, v234
	ds_read_b128 v[48:51], v251 offset:0
	ds_read_b128 v[40:43], v251 offset:4096
	ds_read_b128 v[44:47], v251 offset:2048
	ds_read_b128 v[36:39], v251 offset:6144
	ds_read_b128 v[16:19], v253 offset:0
	ds_read_b128 v[12:15], v253 offset:2048
	ds_read_b128 v[8:11], v253 offset:4096
	ds_read_b128 v[4:7], v253 offset:6144
	ds_read2_b32 v[80:81], v240 offset0:0 offset1:1
	ds_read2_b32 v[82:83], v240 offset0:2 offset1:3
	ds_read2_b32 v[84:85], v240 offset0:4 offset1:5
	ds_read2_b32 v[86:87], v240 offset0:6 offset1:7
	v_mfma_f32_16x16x32_bf16 v[188:191], v[176:179], v[148:151], v[204:207]
	v_mfma_f32_16x16x32_bf16 v[192:195], v[168:171], v[148:151], v[208:211]
	v_mfma_f32_16x16x32_bf16 v[188:191], v[172:175], v[152:155], v[188:191]
	v_mfma_f32_16x16x32_bf16 v[192:195], v[164:167], v[152:155], v[192:195]
	v_mfma_f32_16x16x32_bf16 v[196:199], v[176:179], v[140:143], v[212:215]
	v_mfma_f32_16x16x32_bf16 v[200:203], v[168:171], v[140:143], v[242:245]
	v_mfma_f32_16x16x32_bf16 v[196:199], v[172:175], v[144:147], v[196:199]
	v_mfma_f32_16x16x32_bf16 v[200:203], v[164:167], v[144:147], v[200:203]
	s_nop 2
	v_exp_f32_e32 v188, v188
	v_exp_f32_e32 v189, v189
	v_exp_f32_e32 v190, v190
	v_exp_f32_e32 v191, v191
	v_exp_f32_e32 v192, v192
	v_exp_f32_e32 v193, v193
	v_exp_f32_e32 v194, v194
	v_exp_f32_e32 v195, v195
	v_cvt_pk_bf16_f32 v246, v188, v189
	v_cvt_pk_bf16_f32 v247, v190, v191
	v_cvt_pk_bf16_f32 v248, v192, v193
	v_cvt_pk_bf16_f32 v249, v194, v195
	v_add_f32_e32 v188, v188, v189
	v_add_f32_e32 v190, v190, v191
	v_add_f32_e32 v192, v192, v193
	v_add_f32_e32 v194, v194, v195
	v_add_f32_e32 v188, v188, v190
	v_add_f32_e32 v192, v192, v194
	v_add_f32_e32 v188, v188, v192
	v_add_f32_e32 v224, v224, v188
	v_mfma_f32_16x16x32_bf16 v[188:191], v[176:179], v[132:135], v[180:183]
	v_mfma_f32_16x16x32_bf16 v[192:195], v[168:171], v[132:135], v[184:187]
	v_mfma_f32_16x16x32_bf16 v[188:191], v[172:175], v[136:139], v[188:191]
	v_mfma_f32_16x16x32_bf16 v[192:195], v[164:167], v[136:139], v[192:195]
	v_exp_f32_e32 v196, v196
	v_exp_f32_e32 v197, v197
	v_exp_f32_e32 v198, v198
	v_exp_f32_e32 v199, v199
	v_mfma_f32_16x16x32_bf16 v[128:131], v[32:35], v[246:249], v[128:131]
	v_exp_f32_e32 v200, v200
	v_exp_f32_e32 v201, v201
	v_exp_f32_e32 v202, v202
	v_exp_f32_e32 v203, v203
	v_mfma_f32_16x16x32_bf16 v[124:127], v[28:31], v[246:249], v[124:127]
	v_cvt_pk_bf16_f32 v92, v196, v197
	v_cvt_pk_bf16_f32 v93, v198, v199
	v_cvt_pk_bf16_f32 v94, v200, v201
	v_cvt_pk_bf16_f32 v95, v202, v203
	v_mfma_f32_16x16x32_bf16 v[120:123], v[24:27], v[246:249], v[120:123]
	v_add_f32_e32 v196, v196, v197
	v_add_f32_e32 v198, v198, v199
	v_add_f32_e32 v200, v200, v201
	v_add_f32_e32 v202, v202, v203
	v_mfma_f32_16x16x32_bf16 v[116:119], v[20:23], v[246:249], v[116:119]
	v_add_f32_e32 v196, v196, v198
	v_add_f32_e32 v200, v200, v202
	v_add_f32_e32 v196, v196, v200
	v_add_f32_e32 v223, v223, v196
	v_exp_f32_e32 v188, v188
	v_exp_f32_e32 v189, v189
	v_exp_f32_e32 v190, v190
	v_exp_f32_e32 v191, v191
	v_mfma_f32_16x16x32_bf16 v[64:67], v[32:35], v[92:95], v[64:67]
	v_exp_f32_e32 v192, v192
	v_exp_f32_e32 v193, v193
	v_exp_f32_e32 v194, v194
	v_exp_f32_e32 v195, v195
	v_mfma_f32_16x16x32_bf16 v[60:63], v[28:31], v[92:95], v[60:63]
	v_cvt_pk_bf16_f32 v246, v188, v189
	v_cvt_pk_bf16_f32 v247, v190, v191
	v_cvt_pk_bf16_f32 v248, v192, v193
	v_cvt_pk_bf16_f32 v249, v194, v195
	v_mfma_f32_16x16x32_bf16 v[56:59], v[24:27], v[92:95], v[56:59]
	v_add_f32_e32 v188, v188, v189
	v_add_f32_e32 v190, v190, v191
	v_add_f32_e32 v192, v192, v193
	v_add_f32_e32 v194, v194, v195
	v_mfma_f32_16x16x32_bf16 v[52:55], v[20:23], v[92:95], v[52:55]
	v_add_f32_e32 v188, v188, v190
	v_add_f32_e32 v192, v192, v194
	v_add_f32_e32 v188, v188, v192
	v_add_f32_e32 v222, v222, v188
	s_waitcnt lgkmcnt(0)
	v_sub_f32_e32 v80, v80, v239
	v_sub_f32_e32 v81, v81, v239
	v_sub_f32_e32 v82, v82, v239
	v_mfma_f32_16x16x32_bf16 v[96:99], v[32:35], v[246:249], v[96:99]
	v_sub_f32_e32 v83, v83, v239
	v_sub_f32_e32 v84, v84, v239
	v_sub_f32_e32 v85, v85, v239
	v_mfma_f32_16x16x32_bf16 v[88:91], v[28:31], v[246:249], v[88:91]
	v_sub_f32_e32 v86, v86, v239
	v_sub_f32_e32 v87, v87, v239
	v_cndmask_b32_e64 v80, v238, v80, s[0:1]
	v_mfma_f32_16x16x32_bf16 v[72:75], v[24:27], v[246:249], v[72:75]
	v_cndmask_b32_e64 v81, v238, v81, s[6:7]
	v_cndmask_b32_e64 v82, v238, v82, s[8:9]
	v_cndmask_b32_e64 v83, v238, v83, s[10:11]
	v_mfma_f32_16x16x32_bf16 v[68:71], v[20:23], v[246:249], v[68:71]
	v_cndmask_b32_e64 v84, v238, v84, s[12:13]
	v_cndmask_b32_e64 v85, v238, v85, s[14:15]
	v_cndmask_b32_e64 v86, v238, v86, s[16:17]
	v_cndmask_b32_e64 v87, v238, v87, s[18:19]
	v_add_u32_e32 v240, 0x100, v240
	s_waitcnt lgkmcnt(0)
	s_waitcnt vmcnt(2)
	s_barrier
	s_add_u32 s20, s92, 3
	s_cmp_ge_u32 s20, s88
	s_cbranch_scc1 .Latt_sk9
	s_add_u32 s20, s20, s93
	s_lshl_b32 s21, s20, 16
	s_add_u32 s21, s21, s61
	s_lshl_b32 s22, s20, 7
	s_add_u32 s22, s22, s62
	s_add_u32 m0, s95, s94
	s_add_u32 s84, s95, s94
	s_add_u32 s84, s84, 0x2000
	buffer_load_dwordx4 v241, s[24:27], s21 offen lds
	s_mov_b32 m0, s84
	s_nop 0
	buffer_load_dwordx4 v255, s[40:43], s22 offen lds

.Latt_cs10:
	v_add_u32_e32 v251, s23, v233
	v_add_u32_e32 v253, s33, v234
	ds_read_b128 v[176:179], v251 offset:0
	ds_read_b128 v[168:171], v251 offset:4096
	ds_read_b128 v[172:175], v251 offset:2048
	ds_read_b128 v[164:167], v251 offset:6144
	ds_read_b128 v[32:35], v253 offset:0
	ds_read_b128 v[28:31], v253 offset:2048
	ds_read_b128 v[24:27], v253 offset:4096
	ds_read_b128 v[20:23], v253 offset:6144
	v_mfma_f32_16x16x32_bf16 v[188:191], v[48:51], v[156:159], v[204:207]
	v_mfma_f32_16x16x32_bf16 v[192:195], v[40:43], v[156:159], v[208:211]
	v_mfma_f32_16x16x32_bf16 v[188:191], v[44:47], v[160:163], v[188:191]
	v_mfma_f32_16x16x32_bf16 v[192:195], v[36:39], v[160:163], v[192:195]
	ds_read2_b32 v[204:205], v240 offset0:0 offset1:1
	ds_read2_b32 v[206:207], v240 offset0:2 offset1:3
	ds_read2_b32 v[208:209], v240 offset0:4 offset1:5
	ds_read2_b32 v[210:211], v240 offset0:6 offset1:7
	v_mfma_f32_16x16x32_bf16 v[196:199], v[48:51], v[148:151], v[212:215]
	v_mfma_f32_16x16x32_bf16 v[200:203], v[40:43], v[148:151], v[242:245]
	v_mfma_f32_16x16x32_bf16 v[196:199], v[44:47], v[152:155], v[196:199]
	v_mfma_f32_16x16x32_bf16 v[200:203], v[36:39], v[152:155], v[200:203]
	v_exp_f32_e32 v188, v188
	v_exp_f32_e32 v189, v189
	v_exp_f32_e32 v190, v190
	v_exp_f32_e32 v191, v191
	v_exp_f32_e32 v192, v192
	v_exp_f32_e32 v193, v193
	v_exp_f32_e32 v194, v194
	v_exp_f32_e32 v195, v195
	v_cvt_pk_bf16_f32 v246, v188, v189
	v_cvt_pk_bf16_f32 v247, v190, v191
	v_cvt_pk_bf16_f32 v248, v192, v193
	v_cvt_pk_bf16_f32 v249, v194, v195
	v_add_f32_e32 v188, v188, v189
	v_add_f32_e32 v190, v190, v191
	v_add_f32_e32 v192, v192, v193
	v_add_f32_e32 v194, v194, v195
	v_add_f32_e32 v188, v188, v190
	v_add_f32_e32 v192, v192, v194
	v_add_f32_e32 v188, v188, v192
	v_add_f32_e32 v225, v225, v188
	v_mfma_f32_16x16x32_bf16 v[188:191], v[48:51], v[140:143], v[180:183]
	v_mfma_f32_16x16x32_bf16 v[192:195], v[40:43], v[140:143], v[184:187]
	v_mfma_f32_16x16x32_bf16 v[188:191], v[44:47], v[144:147], v[188:191]
	v_mfma_f32_16x16x32_bf16 v[192:195], v[36:39], v[144:147], v[192:195]
	v_exp_f32_e32 v196, v196
	v_exp_f32_e32 v197, v197
	v_exp_f32_e32 v198, v198
	v_exp_f32_e32 v199, v199
	v_mfma_f32_16x16x32_bf16 v[112:115], v[16:19], v[246:249], v[112:115]
	v_exp_f32_e32 v200, v200
	v_exp_f32_e32 v201, v201
	v_exp_f32_e32 v202, v202
	v_exp_f32_e32 v203, v203
	v_mfma_f32_16x16x32_bf16 v[108:111], v[12:15], v[246:249], v[108:111]
	v_cvt_pk_bf16_f32 v92, v196, v197
	v_cvt_pk_bf16_f32 v93, v198, v199
	v_cvt_pk_bf16_f32 v94, v200, v201
	v_cvt_pk_bf16_f32 v95, v202, v203
	v_mfma_f32_16x16x32_bf16 v[104:107], v[8:11], v[246:249], v[104:107]
	v_add_f32_e32 v196, v196, v197
	v_add_f32_e32 v198, v198, v199
	v_add_f32_e32 v200, v200, v201
	v_add_f32_e32 v202, v202, v203
	v_mfma_f32_16x16x32_bf16 v[100:103], v[4:7], v[246:249], v[100:103]
	v_add_f32_e32 v196, v196, v198
	v_add_f32_e32 v200, v200, v202
	v_add_f32_e32 v196, v196, v200
	v_add_f32_e32 v224, v224, v196
	v_mfma_f32_16x16x32_bf16 v[196:199], v[48:51], v[132:135], v[80:83]
	v_mfma_f32_16x16x32_bf16 v[200:203], v[40:43], v[132:135], v[84:87]
	v_mfma_f32_16x16x32_bf16 v[196:199], v[44:47], v[136:139], v[196:199]
	v_mfma_f32_16x16x32_bf16 v[200:203], v[36:39], v[136:139], v[200:203]
	v_exp_f32_e32 v188, v188
	v_exp_f32_e32 v189, v189
	v_exp_f32_e32 v190, v190
	v_exp_f32_e32 v191, v191
	v_mfma_f32_16x16x32_bf16 v[128:131], v[16:19], v[92:95], v[128:131]
	v_exp_f32_e32 v192, v192
	v_exp_f32_e32 v193, v193
	v_exp_f32_e32 v194, v194
	v_exp_f32_e32 v195, v195
	v_mfma_f32_16x16x32_bf16 v[124:127], v[12:15], v[92:95], v[124:127]
	v_cvt_pk_bf16_f32 v246, v188, v189
	v_cvt_pk_bf16_f32 v247, v190, v191
	v_cvt_pk_bf16_f32 v248, v192, v193
	v_cvt_pk_bf16_f32 v249, v194, v195
	v_mfma_f32_16x16x32_bf16 v[120:123], v[8:11], v[92:95], v[120:123]
	v_add_f32_e32 v188, v188, v189
	v_add_f32_e32 v190, v190, v191
	v_add_f32_e32 v192, v192, v193
	v_add_f32_e32 v194, v194, v195
	v_mfma_f32_16x16x32_bf16 v[116:119], v[4:7], v[92:95], v[116:119]
	v_add_f32_e32 v188, v188, v190
	v_add_f32_e32 v192, v192, v194
	v_add_f32_e32 v188, v188, v192
	v_add_f32_e32 v223, v223, v188
	v_exp_f32_e32 v196, v196
	v_exp_f32_e32 v197, v197
	v_exp_f32_e32 v198, v198
	v_exp_f32_e32 v199, v199
	v_mfma_f32_16x16x32_bf16 v[64:67], v[16:19], v[246:249], v[64:67]
	v_exp_f32_e32 v200, v200
	v_exp_f32_e32 v201, v201
	v_exp_f32_e32 v202, v202
	v_exp_f32_e32 v203, v203
	v_mfma_f32_16x16x32_bf16 v[60:63], v[12:15], v[246:249], v[60:63]
	v_cvt_pk_bf16_f32 v92, v196, v197
	v_cvt_pk_bf16_f32 v93, v198, v199
	v_cvt_pk_bf16_f32 v94, v200, v201
	v_cvt_pk_bf16_f32 v95, v202, v203
	v_mfma_f32_16x16x32_bf16 v[56:59], v[8:11], v[246:249], v[56:59]
	v_add_f32_e32 v196, v196, v197
	v_add_f32_e32 v198, v198, v199
	v_add_f32_e32 v200, v200, v201
	v_add_f32_e32 v202, v202, v203
	v_mfma_f32_16x16x32_bf16 v[52:55], v[4:7], v[246:249], v[52:55]
	v_add_f32_e32 v196, v196, v198
	v_add_f32_e32 v200, v200, v202
	v_add_f32_e32 v196, v196, v200
	v_add_f32_e32 v222, v222, v196
	s_waitcnt lgkmcnt(0)
	v_sub_f32_e32 v204, v204, v239
	v_sub_f32_e32 v205, v205, v239
	v_sub_f32_e32 v206, v206, v239
	v_mfma_f32_16x16x32_bf16 v[96:99], v[16:19], v[92:95], v[96:99]
	v_sub_f32_e32 v207, v207, v239
	v_sub_f32_e32 v208, v208, v239
	v_sub_f32_e32 v209, v209, v239
	v_mfma_f32_16x16x32_bf16 v[88:91], v[12:15], v[92:95], v[88:91]
	v_sub_f32_e32 v210, v210, v239
	v_sub_f32_e32 v211, v211, v239
	v_cndmask_b32_e64 v204, v238, v204, s[0:1]
	v_mfma_f32_16x16x32_bf16 v[72:75], v[8:11], v[92:95], v[72:75]
	v_cndmask_b32_e64 v205, v238, v205, s[6:7]
	v_cndmask_b32_e64 v206, v238, v206, s[8:9]
	v_cndmask_b32_e64 v207, v238, v207, s[10:11]
	v_mfma_f32_16x16x32_bf16 v[68:71], v[4:7], v[92:95], v[68:71]
	v_cndmask_b32_e64 v208, v238, v208, s[12:13]
	v_cndmask_b32_e64 v209, v238, v209, s[14:15]
	v_cndmask_b32_e64 v210, v238, v210, s[16:17]
	v_cndmask_b32_e64 v211, v238, v211, s[18:19]
	v_add_u32_e32 v240, 0x100, v240
	s_waitcnt lgkmcnt(0)
	s_waitcnt vmcnt(2)
	s_barrier
	s_add_u32 s20, s92, 3
	s_cmp_ge_u32 s20, s88
	s_cbranch_scc1 .Latt_sk11
	s_add_u32 s20, s20, s93
	s_lshl_b32 s21, s20, 16
	s_add_u32 s21, s21, s61
	s_lshl_b32 s22, s20, 7
	s_add_u32 s22, s22, s62
	s_add_u32 m0, s95, s94
	s_add_u32 s84, s95, s94
	s_add_u32 s84, s84, 0x2000
	buffer_load_dwordx4 v241, s[24:27], s21 offen lds
	s_mov_b32 m0, s84
	s_nop 0
	buffer_load_dwordx4 v255, s[40:43], s22 offen lds

.Latt_cs12:
	v_add_u32_e32 v251, s23, v233
	v_add_u32_e32 v253, s33, v234
	ds_read_b128 v[48:51], v251 offset:0
	ds_read_b128 v[40:43], v251 offset:4096
	ds_read_b128 v[44:47], v251 offset:2048
	ds_read_b128 v[36:39], v251 offset:6144
	ds_read_b128 v[16:19], v253 offset:0
	ds_read_b128 v[12:15], v253 offset:2048
	ds_read_b128 v[8:11], v253 offset:4096
	ds_read_b128 v[4:7], v253 offset:6144
	v_mfma_f32_16x16x32_bf16 v[188:191], v[176:179], v[156:159], v[212:215]
	v_mfma_f32_16x16x32_bf16 v[192:195], v[168:171], v[156:159], v[242:245]
	v_mfma_f32_16x16x32_bf16 v[188:191], v[172:175], v[160:163], v[188:191]
	v_mfma_f32_16x16x32_bf16 v[192:195], v[164:167], v[160:163], v[192:195]
	ds_read2_b32 v[212:213], v240 offset0:0 offset1:1
	ds_read2_b32 v[214:215], v240 offset0:2 offset1:3
	ds_read2_b32 v[242:243], v240 offset0:4 offset1:5
	ds_read2_b32 v[244:245], v240 offset0:6 offset1:7
	v_mfma_f32_16x16x32_bf16 v[196:199], v[176:179], v[148:151], v[180:183]
	v_mfma_f32_16x16x32_bf16 v[200:203], v[168:171], v[148:151], v[184:187]
	v_mfma_f32_16x16x32_bf16 v[196:199], v[172:175], v[152:155], v[196:199]
	v_mfma_f32_16x16x32_bf16 v[200:203], v[164:167], v[152:155], v[200:203]
	v_exp_f32_e32 v188, v188
	v_exp_f32_e32 v189, v189
	v_exp_f32_e32 v190, v190
	v_exp_f32_e32 v191, v191
	v_exp_f32_e32 v192, v192
	v_exp_f32_e32 v193, v193
	v_exp_f32_e32 v194, v194
	v_exp_f32_e32 v195, v195
	v_cvt_pk_bf16_f32 v246, v188, v189
	v_cvt_pk_bf16_f32 v247, v190, v191
	v_cvt_pk_bf16_f32 v248, v192, v193
	v_cvt_pk_bf16_f32 v249, v194, v195
	v_add_f32_e32 v188, v188, v189
	v_add_f32_e32 v190, v190, v191
	v_add_f32_e32 v192, v192, v193
	v_add_f32_e32 v194, v194, v195
	v_add_f32_e32 v188, v188, v190
	v_add_f32_e32 v192, v192, v194
	v_add_f32_e32 v188, v188, v192
	v_add_f32_e32 v225, v225, v188
	v_mfma_f32_16x16x32_bf16 v[188:191], v[176:179], v[140:143], v[80:83]
	v_mfma_f32_16x16x32_bf16 v[192:195], v[168:171], v[140:143], v[84:87]
	v_mfma_f32_16x16x32_bf16 v[188:191], v[172:175], v[144:147], v[188:191]
	v_mfma_f32_16x16x32_bf16 v[192:195], v[164:167], v[144:147], v[192:195]
	v_exp_f32_e32 v196, v196
	v_exp_f32_e32 v197, v197
	v_exp_f32_e32 v198, v198
	v_exp_f32_e32 v199, v199
	v_mfma_f32_16x16x32_bf16 v[112:115], v[32:35], v[246:249], v[112:115]
	v_exp_f32_e32 v200, v200
	v_exp_f32_e32 v201, v201
	v_exp_f32_e32 v202, v202
	v_exp_f32_e32 v203, v203
	v_mfma_f32_16x16x32_bf16 v[108:111], v[28:31], v[246:249], v[108:111]
	v_cvt_pk_bf16_f32 v92, v196, v197
	v_cvt_pk_bf16_f32 v93, v198, v199
	v_cvt_pk_bf16_f32 v94, v200, v201
	v_cvt_pk_bf16_f32 v95, v202, v203
	v_mfma_f32_16x16x32_bf16 v[104:107], v[24:27], v[246:249], v[104:107]
	v_add_f32_e32 v196, v196, v197
	v_add_f32_e32 v198, v198, v199
	v_add_f32_e32 v200, v200, v201
	v_add_f32_e32 v202, v202, v203
	v_mfma_f32_16x16x32_bf16 v[100:103], v[20:23], v[246:249], v[100:103]
	v_add_f32_e32 v196, v196, v198
	v_add_f32_e32 v200, v200, v202
	v_add_f32_e32 v196, v196, v200
	v_add_f32_e32 v224, v224, v196
	v_mfma_f32_16x16x32_bf16 v[196:199], v[176:179], v[132:135], v[204:207]
	v_mfma_f32_16x16x32_bf16 v[200:203], v[168:171], v[132:135], v[208:211]
	v_mfma_f32_16x16x32_bf16 v[196:199], v[172:175], v[136:139], v[196:199]
	v_mfma_f32_16x16x32_bf16 v[200:203], v[164:167], v[136:139], v[200:203]
	v_exp_f32_e32 v188, v188
	v_exp_f32_e32 v189, v189
	v_exp_f32_e32 v190, v190
	v_exp_f32_e32 v191, v191
	v_mfma_f32_16x16x32_bf16 v[128:131], v[32:35], v[92:95], v[128:131]
	v_exp_f32_e32 v192, v192
	v_exp_f32_e32 v193, v193
	v_exp_f32_e32 v194, v194
	v_exp_f32_e32 v195, v195
	v_mfma_f32_16x16x32_bf16 v[124:127], v[28:31], v[92:95], v[124:127]
	v_cvt_pk_bf16_f32 v246, v188, v189
	v_cvt_pk_bf16_f32 v247, v190, v191
	v_cvt_pk_bf16_f32 v248, v192, v193
	v_cvt_pk_bf16_f32 v249, v194, v195
	v_mfma_f32_16x16x32_bf16 v[120:123], v[24:27], v[92:95], v[120:123]
	v_add_f32_e32 v188, v188, v189
	v_add_f32_e32 v190, v190, v191
	v_add_f32_e32 v192, v192, v193
	v_add_f32_e32 v194, v194, v195
	v_mfma_f32_16x16x32_bf16 v[116:119], v[20:23], v[92:95], v[116:119]
	v_add_f32_e32 v188, v188, v190
	v_add_f32_e32 v192, v192, v194
	v_add_f32_e32 v188, v188, v192
	v_add_f32_e32 v223, v223, v188
	v_exp_f32_e32 v196, v196
	v_exp_f32_e32 v197, v197
	v_exp_f32_e32 v198, v198
	v_exp_f32_e32 v199, v199
	v_mfma_f32_16x16x32_bf16 v[64:67], v[32:35], v[246:249], v[64:67]
	v_exp_f32_e32 v200, v200
	v_exp_f32_e32 v201, v201
	v_exp_f32_e32 v202, v202
	v_exp_f32_e32 v203, v203
	v_mfma_f32_16x16x32_bf16 v[60:63], v[28:31], v[246:249], v[60:63]
	v_cvt_pk_bf16_f32 v92, v196, v197
	v_cvt_pk_bf16_f32 v93, v198, v199
	v_cvt_pk_bf16_f32 v94, v200, v201
	v_cvt_pk_bf16_f32 v95, v202, v203
	v_mfma_f32_16x16x32_bf16 v[56:59], v[24:27], v[246:249], v[56:59]
	v_add_f32_e32 v196, v196, v197
	v_add_f32_e32 v198, v198, v199
	v_add_f32_e32 v200, v200, v201
	v_add_f32_e32 v202, v202, v203
	v_mfma_f32_16x16x32_bf16 v[52:55], v[20:23], v[246:249], v[52:55]
	v_add_f32_e32 v196, v196, v198
	v_add_f32_e32 v200, v200, v202
	v_add_f32_e32 v196, v196, v200
	v_add_f32_e32 v222, v222, v196
	s_waitcnt lgkmcnt(0)
	v_sub_f32_e32 v212, v212, v239
	v_sub_f32_e32 v213, v213, v239
	v_sub_f32_e32 v214, v214, v239
	v_mfma_f32_16x16x32_bf16 v[96:99], v[32:35], v[92:95], v[96:99]
	v_sub_f32_e32 v215, v215, v239
	v_sub_f32_e32 v242, v242, v239
	v_sub_f32_e32 v243, v243, v239
	v_mfma_f32_16x16x32_bf16 v[88:91], v[28:31], v[92:95], v[88:91]
	v_sub_f32_e32 v244, v244, v239
	v_sub_f32_e32 v245, v245, v239
	v_cndmask_b32_e64 v212, v238, v212, s[0:1]
	v_mfma_f32_16x16x32_bf16 v[72:75], v[24:27], v[92:95], v[72:75]
	v_cndmask_b32_e64 v213, v238, v213, s[6:7]
	v_cndmask_b32_e64 v214, v238, v214, s[8:9]
	v_cndmask_b32_e64 v215, v238, v215, s[10:11]
	v_mfma_f32_16x16x32_bf16 v[68:71], v[20:23], v[92:95], v[68:71]
	v_cndmask_b32_e64 v242, v238, v242, s[12:13]
	v_cndmask_b32_e64 v243, v238, v243, s[14:15]
	v_cndmask_b32_e64 v244, v238, v244, s[16:17]
	v_cndmask_b32_e64 v245, v238, v245, s[18:19]
	v_add_u32_e32 v240, 0x100, v240
	s_waitcnt lgkmcnt(0)
	s_waitcnt vmcnt(2)
	s_barrier
	s_add_u32 s20, s92, 3
	s_cmp_ge_u32 s20, s88
	s_cbranch_scc1 .Latt_sk13
	s_add_u32 s20, s20, s93
	s_lshl_b32 s21, s20, 16
	s_add_u32 s21, s21, s61
	s_lshl_b32 s22, s20, 7
	s_add_u32 s22, s22, s62
	s_add_u32 m0, s95, s94
	s_add_u32 s84, s95, s94
	s_add_u32 s84, s84, 0x2000
	buffer_load_dwordx4 v241, s[24:27], s21 offen lds
	s_mov_b32 m0, s84
	s_nop 0
	buffer_load_dwordx4 v255, s[40:43], s22 offen lds

.Latt_cs14:
	v_add_u32_e32 v251, s23, v233
	v_add_u32_e32 v253, s33, v234
	ds_read_b128 v[176:179], v251 offset:0
	ds_read_b128 v[168:171], v251 offset:4096
	ds_read_b128 v[172:175], v251 offset:2048
	ds_read_b128 v[164:167], v251 offset:6144
	ds_read_b128 v[32:35], v253 offset:0
	ds_read_b128 v[28:31], v253 offset:2048
	ds_read_b128 v[24:27], v253 offset:4096
	ds_read_b128 v[20:23], v253 offset:6144
	v_mfma_f32_16x16x32_bf16 v[188:191], v[48:51], v[156:159], v[180:183]
	v_mfma_f32_16x16x32_bf16 v[192:195], v[40:43], v[156:159], v[184:187]
	v_mfma_f32_16x16x32_bf16 v[188:191], v[44:47], v[160:163], v[188:191]
	v_mfma_f32_16x16x32_bf16 v[192:195], v[36:39], v[160:163], v[192:195]
	ds_read2_b32 v[180:181], v240 offset0:0 offset1:1
	ds_read2_b32 v[182:183], v240 offset0:2 offset1:3
	ds_read2_b32 v[184:185], v240 offset0:4 offset1:5
	ds_read2_b32 v[186:187], v240 offset0:6 offset1:7
	v_mfma_f32_16x16x32_bf16 v[196:199], v[48:51], v[148:151], v[80:83]
	v_mfma_f32_16x16x32_bf16 v[200:203], v[40:43], v[148:151], v[84:87]
	v_mfma_f32_16x16x32_bf16 v[196:199], v[44:47], v[152:155], v[196:199]
	v_mfma_f32_16x16x32_bf16 v[200:203], v[36:39], v[152:155], v[200:203]
	v_exp_f32_e32 v188, v188
	v_exp_f32_e32 v189, v189
	v_exp_f32_e32 v190, v190
	v_exp_f32_e32 v191, v191
	v_exp_f32_e32 v192, v192
	v_exp_f32_e32 v193, v193
	v_exp_f32_e32 v194, v194
	v_exp_f32_e32 v195, v195
	v_cvt_pk_bf16_f32 v246, v188, v189
	v_cvt_pk_bf16_f32 v247, v190, v191
	v_cvt_pk_bf16_f32 v248, v192, v193
	v_cvt_pk_bf16_f32 v249, v194, v195
	v_add_f32_e32 v188, v188, v189
	v_add_f32_e32 v190, v190, v191
	v_add_f32_e32 v192, v192, v193
	v_add_f32_e32 v194, v194, v195
	v_add_f32_e32 v188, v188, v190
	v_add_f32_e32 v192, v192, v194
	v_add_f32_e32 v188, v188, v192
	v_add_f32_e32 v225, v225, v188
	v_mfma_f32_16x16x32_bf16 v[188:191], v[48:51], v[140:143], v[204:207]
	v_mfma_f32_16x16x32_bf16 v[192:195], v[40:43], v[140:143], v[208:211]
	v_mfma_f32_16x16x32_bf16 v[188:191], v[44:47], v[144:147], v[188:191]
	v_mfma_f32_16x16x32_bf16 v[192:195], v[36:39], v[144:147], v[192:195]
	v_exp_f32_e32 v196, v196
	v_exp_f32_e32 v197, v197
	v_exp_f32_e32 v198, v198
	v_exp_f32_e32 v199, v199
	v_mfma_f32_16x16x32_bf16 v[112:115], v[16:19], v[246:249], v[112:115]
	v_exp_f32_e32 v200, v200
	v_exp_f32_e32 v201, v201
	v_exp_f32_e32 v202, v202
	v_exp_f32_e32 v203, v203
	v_mfma_f32_16x16x32_bf16 v[108:111], v[12:15], v[246:249], v[108:111]
	v_cvt_pk_bf16_f32 v92, v196, v197
	v_cvt_pk_bf16_f32 v93, v198, v199
	v_cvt_pk_bf16_f32 v94, v200, v201
	v_cvt_pk_bf16_f32 v95, v202, v203
	v_mfma_f32_16x16x32_bf16 v[104:107], v[8:11], v[246:249], v[104:107]
	v_add_f32_e32 v196, v196, v197
	v_add_f32_e32 v198, v198, v199
	v_add_f32_e32 v200, v200, v201
	v_add_f32_e32 v202, v202, v203
	v_mfma_f32_16x16x32_bf16 v[100:103], v[4:7], v[246:249], v[100:103]
	v_add_f32_e32 v196, v196, v198
	v_add_f32_e32 v200, v200, v202
	v_add_f32_e32 v196, v196, v200
	v_add_f32_e32 v224, v224, v196
	v_mfma_f32_16x16x32_bf16 v[196:199], v[48:51], v[132:135], v[212:215]
	v_mfma_f32_16x16x32_bf16 v[200:203], v[40:43], v[132:135], v[242:245]
	v_mfma_f32_16x16x32_bf16 v[196:199], v[44:47], v[136:139], v[196:199]
	v_mfma_f32_16x16x32_bf16 v[200:203], v[36:39], v[136:139], v[200:203]
	v_exp_f32_e32 v188, v188
	v_exp_f32_e32 v189, v189
	v_exp_f32_e32 v190, v190
	v_exp_f32_e32 v191, v191
	v_mfma_f32_16x16x32_bf16 v[128:131], v[16:19], v[92:95], v[128:131]
	v_exp_f32_e32 v192, v192
	v_exp_f32_e32 v193, v193
	v_exp_f32_e32 v194, v194
	v_exp_f32_e32 v195, v195
	v_mfma_f32_16x16x32_bf16 v[124:127], v[12:15], v[92:95], v[124:127]
	v_cvt_pk_bf16_f32 v246, v188, v189
	v_cvt_pk_bf16_f32 v247, v190, v191
	v_cvt_pk_bf16_f32 v248, v192, v193
	v_cvt_pk_bf16_f32 v249, v194, v195
	v_mfma_f32_16x16x32_bf16 v[120:123], v[8:11], v[92:95], v[120:123]
	v_add_f32_e32 v188, v188, v189
	v_add_f32_e32 v190, v190, v191
	v_add_f32_e32 v192, v192, v193
	v_add_f32_e32 v194, v194, v195
	v_mfma_f32_16x16x32_bf16 v[116:119], v[4:7], v[92:95], v[116:119]
	v_add_f32_e32 v188, v188, v190
	v_add_f32_e32 v192, v192, v194
	v_add_f32_e32 v188, v188, v192
	v_add_f32_e32 v223, v223, v188
	v_exp_f32_e32 v196, v196
	v_exp_f32_e32 v197, v197
	v_exp_f32_e32 v198, v198
	v_exp_f32_e32 v199, v199
	v_mfma_f32_16x16x32_bf16 v[64:67], v[16:19], v[246:249], v[64:67]
	v_exp_f32_e32 v200, v200
	v_exp_f32_e32 v201, v201
	v_exp_f32_e32 v202, v202
	v_exp_f32_e32 v203, v203
	v_mfma_f32_16x16x32_bf16 v[60:63], v[12:15], v[246:249], v[60:63]
	v_cvt_pk_bf16_f32 v92, v196, v197
	v_cvt_pk_bf16_f32 v93, v198, v199
	v_cvt_pk_bf16_f32 v94, v200, v201
	v_cvt_pk_bf16_f32 v95, v202, v203
	v_mfma_f32_16x16x32_bf16 v[56:59], v[8:11], v[246:249], v[56:59]
	v_add_f32_e32 v196, v196, v197
	v_add_f32_e32 v198, v198, v199
	v_add_f32_e32 v200, v200, v201
	v_add_f32_e32 v202, v202, v203
	v_mfma_f32_16x16x32_bf16 v[52:55], v[4:7], v[246:249], v[52:55]
	v_add_f32_e32 v196, v196, v198
	v_add_f32_e32 v200, v200, v202
	v_add_f32_e32 v196, v196, v200
	v_add_f32_e32 v222, v222, v196
	s_waitcnt lgkmcnt(0)
	v_sub_f32_e32 v180, v180, v239
	v_sub_f32_e32 v181, v181, v239
	v_sub_f32_e32 v182, v182, v239
	v_mfma_f32_16x16x32_bf16 v[96:99], v[16:19], v[92:95], v[96:99]
	v_sub_f32_e32 v183, v183, v239
	v_sub_f32_e32 v184, v184, v239
	v_sub_f32_e32 v185, v185, v239
	v_mfma_f32_16x16x32_bf16 v[88:91], v[12:15], v[92:95], v[88:91]
	v_sub_f32_e32 v186, v186, v239
	v_sub_f32_e32 v187, v187, v239
	v_cndmask_b32_e64 v180, v238, v180, s[0:1]
	v_mfma_f32_16x16x32_bf16 v[72:75], v[8:11], v[92:95], v[72:75]
	v_cndmask_b32_e64 v181, v238, v181, s[6:7]
	v_cndmask_b32_e64 v182, v238, v182, s[8:9]
	v_cndmask_b32_e64 v183, v238, v183, s[10:11]
	v_mfma_f32_16x16x32_bf16 v[68:71], v[4:7], v[92:95], v[68:71]
	v_cndmask_b32_e64 v184, v238, v184, s[12:13]
	v_cndmask_b32_e64 v185, v238, v185, s[14:15]
	v_cndmask_b32_e64 v186, v238, v186, s[16:17]
	v_cndmask_b32_e64 v187, v238, v187, s[18:19]
	v_add_u32_e32 v240, 0x100, v240
	s_waitcnt lgkmcnt(0)
	s_waitcnt vmcnt(2)
	s_barrier
	s_add_u32 s20, s92, 3
	s_cmp_ge_u32 s20, s88
	s_cbranch_scc1 .Latt_sk15
	s_add_u32 s20, s20, s93
	s_lshl_b32 s21, s20, 16
	s_add_u32 s21, s21, s61
	s_lshl_b32 s22, s20, 7
	s_add_u32 s22, s22, s62
	s_add_u32 m0, s95, s94
	s_add_u32 s84, s95, s94
	s_add_u32 s84, s84, 0x2000
	buffer_load_dwordx4 v241, s[24:27], s21 offen lds
	s_mov_b32 m0, s84
	s_nop 0
	buffer_load_dwordx4 v255, s[40:43], s22 offen lds

.Latt_cs16:
	v_add_u32_e32 v251, s23, v233
	v_add_u32_e32 v253, s33, v234
	ds_read_b128 v[48:51], v251 offset:0
	ds_read_b128 v[40:43], v251 offset:4096
	ds_read_b128 v[44:47], v251 offset:2048
	ds_read_b128 v[36:39], v251 offset:6144
	ds_read_b128 v[16:19], v253 offset:0
	ds_read_b128 v[12:15], v253 offset:2048
	ds_read_b128 v[8:11], v253 offset:4096
	ds_read_b128 v[4:7], v253 offset:6144
	v_mfma_f32_16x16x32_bf16 v[188:191], v[176:179], v[156:159], v[80:83]
	v_mfma_f32_16x16x32_bf16 v[192:195], v[168:171], v[156:159], v[84:87]
	v_mfma_f32_16x16x32_bf16 v[188:191], v[172:175], v[160:163], v[188:191]
	v_mfma_f32_16x16x32_bf16 v[192:195], v[164:167], v[160:163], v[192:195]
	ds_read2_b32 v[80:81], v240 offset0:0 offset1:1
	ds_read2_b32 v[82:83], v240 offset0:2 offset1:3
	ds_read2_b32 v[84:85], v240 offset0:4 offset1:5
	ds_read2_b32 v[86:87], v240 offset0:6 offset1:7
	v_mfma_f32_16x16x32_bf16 v[196:199], v[176:179], v[148:151], v[204:207]
	v_mfma_f32_16x16x32_bf16 v[200:203], v[168:171], v[148:151], v[208:211]
	v_mfma_f32_16x16x32_bf16 v[196:199], v[172:175], v[152:155], v[196:199]
	v_mfma_f32_16x16x32_bf16 v[200:203], v[164:167], v[152:155], v[200:203]
	v_exp_f32_e32 v188, v188
	v_exp_f32_e32 v189, v189
	v_exp_f32_e32 v190, v190
	v_exp_f32_e32 v191, v191
	v_exp_f32_e32 v192, v192
	v_exp_f32_e32 v193, v193
	v_exp_f32_e32 v194, v194
	v_exp_f32_e32 v195, v195
	v_cvt_pk_bf16_f32 v246, v188, v189
	v_cvt_pk_bf16_f32 v247, v190, v191
	v_cvt_pk_bf16_f32 v248, v192, v193
	v_cvt_pk_bf16_f32 v249, v194, v195
	v_add_f32_e32 v188, v188, v189
	v_add_f32_e32 v190, v190, v191
	v_add_f32_e32 v192, v192, v193
	v_add_f32_e32 v194, v194, v195
	v_add_f32_e32 v188, v188, v190
	v_add_f32_e32 v192, v192, v194
	v_add_f32_e32 v188, v188, v192
	v_add_f32_e32 v225, v225, v188
	v_mfma_f32_16x16x32_bf16 v[188:191], v[176:179], v[140:143], v[212:215]
	v_mfma_f32_16x16x32_bf16 v[192:195], v[168:171], v[140:143], v[242:245]
	v_mfma_f32_16x16x32_bf16 v[188:191], v[172:175], v[144:147], v[188:191]
	v_mfma_f32_16x16x32_bf16 v[192:195], v[164:167], v[144:147], v[192:195]
	v_exp_f32_e32 v196, v196
	v_exp_f32_e32 v197, v197
	v_exp_f32_e32 v198, v198
	v_exp_f32_e32 v199, v199
	v_mfma_f32_16x16x32_bf16 v[112:115], v[32:35], v[246:249], v[112:115]
	v_exp_f32_e32 v200, v200
	v_exp_f32_e32 v201, v201
	v_exp_f32_e32 v202, v202
	v_exp_f32_e32 v203, v203
	v_mfma_f32_16x16x32_bf16 v[108:111], v[28:31], v[246:249], v[108:111]
	v_cvt_pk_bf16_f32 v92, v196, v197
	v_cvt_pk_bf16_f32 v93, v198, v199
	v_cvt_pk_bf16_f32 v94, v200, v201
	v_cvt_pk_bf16_f32 v95, v202, v203
	v_mfma_f32_16x16x32_bf16 v[104:107], v[24:27], v[246:249], v[104:107]
	v_add_f32_e32 v196, v196, v197
	v_add_f32_e32 v198, v198, v199
	v_add_f32_e32 v200, v200, v201
	v_add_f32_e32 v202, v202, v203
	v_mfma_f32_16x16x32_bf16 v[100:103], v[20:23], v[246:249], v[100:103]
	v_add_f32_e32 v196, v196, v198
	v_add_f32_e32 v200, v200, v202
	v_add_f32_e32 v196, v196, v200
	v_add_f32_e32 v224, v224, v196
	v_mfma_f32_16x16x32_bf16 v[196:199], v[176:179], v[132:135], v[180:183]
	v_mfma_f32_16x16x32_bf16 v[200:203], v[168:171], v[132:135], v[184:187]
	v_mfma_f32_16x16x32_bf16 v[196:199], v[172:175], v[136:139], v[196:199]
	v_mfma_f32_16x16x32_bf16 v[200:203], v[164:167], v[136:139], v[200:203]
	v_exp_f32_e32 v188, v188
	v_exp_f32_e32 v189, v189
	v_exp_f32_e32 v190, v190
	v_exp_f32_e32 v191, v191
	v_mfma_f32_16x16x32_bf16 v[128:131], v[32:35], v[92:95], v[128:131]
	v_exp_f32_e32 v192, v192
	v_exp_f32_e32 v193, v193
	v_exp_f32_e32 v194, v194
	v_exp_f32_e32 v195, v195
	v_mfma_f32_16x16x32_bf16 v[124:127], v[28:31], v[92:95], v[124:127]
	v_cvt_pk_bf16_f32 v246, v188, v189
	v_cvt_pk_bf16_f32 v247, v190, v191
	v_cvt_pk_bf16_f32 v248, v192, v193
	v_cvt_pk_bf16_f32 v249, v194, v195
	v_mfma_f32_16x16x32_bf16 v[120:123], v[24:27], v[92:95], v[120:123]
	v_add_f32_e32 v188, v188, v189
	v_add_f32_e32 v190, v190, v191
	v_add_f32_e32 v192, v192, v193
	v_add_f32_e32 v194, v194, v195
	v_mfma_f32_16x16x32_bf16 v[116:119], v[20:23], v[92:95], v[116:119]
	v_add_f32_e32 v188, v188, v190
	v_add_f32_e32 v192, v192, v194
	v_add_f32_e32 v188, v188, v192
	v_add_f32_e32 v223, v223, v188
	v_exp_f32_e32 v196, v196
	v_exp_f32_e32 v197, v197
	v_exp_f32_e32 v198, v198
	v_exp_f32_e32 v199, v199
	v_mfma_f32_16x16x32_bf16 v[64:67], v[32:35], v[246:249], v[64:67]
	v_exp_f32_e32 v200, v200
	v_exp_f32_e32 v201, v201
	v_exp_f32_e32 v202, v202
	v_exp_f32_e32 v203, v203
	v_mfma_f32_16x16x32_bf16 v[60:63], v[28:31], v[246:249], v[60:63]
	v_cvt_pk_bf16_f32 v92, v196, v197
	v_cvt_pk_bf16_f32 v93, v198, v199
	v_cvt_pk_bf16_f32 v94, v200, v201
	v_cvt_pk_bf16_f32 v95, v202, v203
	v_mfma_f32_16x16x32_bf16 v[56:59], v[24:27], v[246:249], v[56:59]
	v_add_f32_e32 v196, v196, v197
	v_add_f32_e32 v198, v198, v199
	v_add_f32_e32 v200, v200, v201
	v_add_f32_e32 v202, v202, v203
	v_mfma_f32_16x16x32_bf16 v[52:55], v[20:23], v[246:249], v[52:55]
	v_add_f32_e32 v196, v196, v198
	v_add_f32_e32 v200, v200, v202
	v_add_f32_e32 v196, v196, v200
	v_add_f32_e32 v222, v222, v196
	s_waitcnt lgkmcnt(0)
	v_sub_f32_e32 v80, v80, v239
	v_sub_f32_e32 v81, v81, v239
	v_sub_f32_e32 v82, v82, v239
	v_mfma_f32_16x16x32_bf16 v[96:99], v[32:35], v[92:95], v[96:99]
	v_sub_f32_e32 v83, v83, v239
	v_sub_f32_e32 v84, v84, v239
	v_sub_f32_e32 v85, v85, v239
	v_mfma_f32_16x16x32_bf16 v[88:91], v[28:31], v[92:95], v[88:91]
	v_sub_f32_e32 v86, v86, v239
	v_sub_f32_e32 v87, v87, v239
	v_cndmask_b32_e64 v80, v238, v80, s[0:1]
	v_mfma_f32_16x16x32_bf16 v[72:75], v[24:27], v[92:95], v[72:75]
	v_cndmask_b32_e64 v81, v238, v81, s[6:7]
	v_cndmask_b32_e64 v82, v238, v82, s[8:9]
	v_cndmask_b32_e64 v83, v238, v83, s[10:11]
	v_mfma_f32_16x16x32_bf16 v[68:71], v[20:23], v[92:95], v[68:71]
	v_cndmask_b32_e64 v84, v238, v84, s[12:13]
	v_cndmask_b32_e64 v85, v238, v85, s[14:15]
	v_cndmask_b32_e64 v86, v238, v86, s[16:17]
	v_cndmask_b32_e64 v87, v238, v87, s[18:19]
	v_add_u32_e32 v240, 0x100, v240
	s_waitcnt lgkmcnt(0)
	s_waitcnt vmcnt(2)
	s_barrier
	s_add_u32 s20, s92, 3
	s_cmp_ge_u32 s20, s88
	s_cbranch_scc1 .Latt_sk17
	s_add_u32 s20, s20, s93
	s_lshl_b32 s21, s20, 16
	s_add_u32 s21, s21, s61
	s_lshl_b32 s22, s20, 7
	s_add_u32 s22, s22, s62
	s_add_u32 m0, s95, s94
	s_add_u32 s84, s95, s94
	s_add_u32 s84, s84, 0x2000
	buffer_load_dwordx4 v241, s[24:27], s21 offen lds
	s_mov_b32 m0, s84
	s_nop 0
	buffer_load_dwordx4 v255, s[40:43], s22 offen lds

.Latt_cs18:
	v_add_u32_e32 v251, s23, v233
	v_add_u32_e32 v253, s33, v234
	ds_read_b128 v[176:179], v251 offset:0
	ds_read_b128 v[168:171], v251 offset:4096
	ds_read_b128 v[172:175], v251 offset:2048
	ds_read_b128 v[164:167], v251 offset:6144
	ds_read_b128 v[32:35], v253 offset:0
	ds_read_b128 v[28:31], v253 offset:2048
	ds_read_b128 v[24:27], v253 offset:4096
	ds_read_b128 v[20:23], v253 offset:6144
	v_mfma_f32_16x16x32_bf16 v[188:191], v[48:51], v[156:159], v[204:207]
	v_mfma_f32_16x16x32_bf16 v[192:195], v[40:43], v[156:159], v[208:211]
	v_mfma_f32_16x16x32_bf16 v[188:191], v[44:47], v[160:163], v[188:191]
	v_mfma_f32_16x16x32_bf16 v[192:195], v[36:39], v[160:163], v[192:195]
	v_mfma_f32_16x16x32_bf16 v[196:199], v[48:51], v[148:151], v[212:215]
	v_mfma_f32_16x16x32_bf16 v[200:203], v[40:43], v[148:151], v[242:245]
	v_mfma_f32_16x16x32_bf16 v[196:199], v[44:47], v[152:155], v[196:199]
	v_mfma_f32_16x16x32_bf16 v[200:203], v[36:39], v[152:155], v[200:203]
	s_nop 2
	v_exp_f32_e32 v188, v188
	v_exp_f32_e32 v189, v189
	v_exp_f32_e32 v190, v190
	v_exp_f32_e32 v191, v191
	v_exp_f32_e32 v192, v192
	v_exp_f32_e32 v193, v193
	v_exp_f32_e32 v194, v194
	v_exp_f32_e32 v195, v195
	v_cvt_pk_bf16_f32 v246, v188, v189
	v_cvt_pk_bf16_f32 v247, v190, v191
	v_cvt_pk_bf16_f32 v248, v192, v193
	v_cvt_pk_bf16_f32 v249, v194, v195
	v_add_f32_e32 v188, v188, v189
	v_add_f32_e32 v190, v190, v191
	v_add_f32_e32 v192, v192, v193
	v_add_f32_e32 v194, v194, v195
	v_add_f32_e32 v188, v188, v190
	v_add_f32_e32 v192, v192, v194
	v_add_f32_e32 v188, v188, v192
	v_add_f32_e32 v225, v225, v188
	v_mfma_f32_16x16x32_bf16 v[188:191], v[48:51], v[140:143], v[180:183]
	v_mfma_f32_16x16x32_bf16 v[192:195], v[40:43], v[140:143], v[184:187]
	v_mfma_f32_16x16x32_bf16 v[188:191], v[44:47], v[144:147], v[188:191]
	v_mfma_f32_16x16x32_bf16 v[192:195], v[36:39], v[144:147], v[192:195]
	v_exp_f32_e32 v196, v196
	v_exp_f32_e32 v197, v197
	v_exp_f32_e32 v198, v198
	v_exp_f32_e32 v199, v199
	v_mfma_f32_16x16x32_bf16 v[112:115], v[16:19], v[246:249], v[112:115]
	v_exp_f32_e32 v200, v200
	v_exp_f32_e32 v201, v201
	v_exp_f32_e32 v202, v202
	v_exp_f32_e32 v203, v203
	v_mfma_f32_16x16x32_bf16 v[108:111], v[12:15], v[246:249], v[108:111]
	v_cvt_pk_bf16_f32 v92, v196, v197
	v_cvt_pk_bf16_f32 v93, v198, v199
	v_cvt_pk_bf16_f32 v94, v200, v201
	v_cvt_pk_bf16_f32 v95, v202, v203
	v_mfma_f32_16x16x32_bf16 v[104:107], v[8:11], v[246:249], v[104:107]
	v_add_f32_e32 v196, v196, v197
	v_add_f32_e32 v198, v198, v199
	v_add_f32_e32 v200, v200, v201
	v_add_f32_e32 v202, v202, v203
	v_mfma_f32_16x16x32_bf16 v[100:103], v[4:7], v[246:249], v[100:103]
	v_add_f32_e32 v196, v196, v198
	v_add_f32_e32 v200, v200, v202
	v_add_f32_e32 v196, v196, v200
	v_add_f32_e32 v224, v224, v196
	v_mfma_f32_16x16x32_bf16 v[196:199], v[48:51], v[132:135], v[80:83]
	v_mfma_f32_16x16x32_bf16 v[200:203], v[40:43], v[132:135], v[84:87]
	v_mfma_f32_16x16x32_bf16 v[196:199], v[44:47], v[136:139], v[196:199]
	v_mfma_f32_16x16x32_bf16 v[200:203], v[36:39], v[136:139], v[200:203]
	v_exp_f32_e32 v188, v188
	v_exp_f32_e32 v189, v189
	v_exp_f32_e32 v190, v190
	v_exp_f32_e32 v191, v191
	v_mfma_f32_16x16x32_bf16 v[128:131], v[16:19], v[92:95], v[128:131]
	v_exp_f32_e32 v192, v192
	v_exp_f32_e32 v193, v193
	v_exp_f32_e32 v194, v194
	v_exp_f32_e32 v195, v195
	v_mfma_f32_16x16x32_bf16 v[124:127], v[12:15], v[92:95], v[124:127]
	v_cvt_pk_bf16_f32 v246, v188, v189
	v_cvt_pk_bf16_f32 v247, v190, v191
	v_cvt_pk_bf16_f32 v248, v192, v193
	v_cvt_pk_bf16_f32 v249, v194, v195
	v_mfma_f32_16x16x32_bf16 v[120:123], v[8:11], v[92:95], v[120:123]
	v_add_f32_e32 v188, v188, v189
	v_add_f32_e32 v190, v190, v191
	v_add_f32_e32 v192, v192, v193
	v_add_f32_e32 v194, v194, v195
	v_mfma_f32_16x16x32_bf16 v[116:119], v[4:7], v[92:95], v[116:119]
	v_add_f32_e32 v188, v188, v190
	v_add_f32_e32 v192, v192, v194
	v_add_f32_e32 v188, v188, v192
	v_add_f32_e32 v223, v223, v188
	v_exp_f32_e32 v196, v196
	v_exp_f32_e32 v197, v197
	v_exp_f32_e32 v198, v198
	v_exp_f32_e32 v199, v199
	v_mfma_f32_16x16x32_bf16 v[64:67], v[16:19], v[246:249], v[64:67]
	v_exp_f32_e32 v200, v200
	v_exp_f32_e32 v201, v201
	v_exp_f32_e32 v202, v202
	v_exp_f32_e32 v203, v203
	v_mfma_f32_16x16x32_bf16 v[60:63], v[12:15], v[246:249], v[60:63]
	v_cvt_pk_bf16_f32 v92, v196, v197
	v_cvt_pk_bf16_f32 v93, v198, v199
	v_cvt_pk_bf16_f32 v94, v200, v201
	v_cvt_pk_bf16_f32 v95, v202, v203
	v_mfma_f32_16x16x32_bf16 v[56:59], v[8:11], v[246:249], v[56:59]
	v_add_f32_e32 v196, v196, v197
	v_add_f32_e32 v198, v198, v199
	v_add_f32_e32 v200, v200, v201
	v_add_f32_e32 v202, v202, v203
	v_mfma_f32_16x16x32_bf16 v[52:55], v[4:7], v[246:249], v[52:55]
	v_add_f32_e32 v196, v196, v198
	v_add_f32_e32 v200, v200, v202
	v_add_f32_e32 v196, v196, v200
	v_add_f32_e32 v222, v222, v196
	v_mfma_f32_16x16x32_bf16 v[96:99], v[16:19], v[92:95], v[96:99]
	v_mfma_f32_16x16x32_bf16 v[88:91], v[12:15], v[92:95], v[88:91]
	v_mfma_f32_16x16x32_bf16 v[72:75], v[8:11], v[92:95], v[72:75]
	v_mfma_f32_16x16x32_bf16 v[68:71], v[4:7], v[92:95], v[68:71]
	v_add_u32_e32 v240, 0x100, v240
	s_waitcnt lgkmcnt(0)
	s_waitcnt vmcnt(2)
	s_barrier
	s_add_u32 s20, s92, 3
	s_cmp_ge_u32 s20, s88
	s_cbranch_scc1 .Latt_sk19
	s_add_u32 s20, s20, s93
	s_lshl_b32 s21, s20, 16
	s_add_u32 s21, s21, s61
	s_lshl_b32 s22, s20, 7
	s_add_u32 s22, s22, s62
	s_add_u32 m0, s95, s94
	s_add_u32 s84, s95, s94
	s_add_u32 s84, s84, 0x2000
	buffer_load_dwordx4 v241, s[24:27], s21 offen lds
	s_mov_b32 m0, s84
	s_nop 0
	buffer_load_dwordx4 v255, s[40:43], s22 offen lds

.Latt_cs20:
	v_add_u32_e32 v251, s23, v233
	v_add_u32_e32 v253, s33, v234
	ds_read_b128 v[48:51], v251 offset:0
	ds_read_b128 v[40:43], v251 offset:4096
	ds_read_b128 v[44:47], v251 offset:2048
	ds_read_b128 v[36:39], v251 offset:6144
	ds_read_b128 v[16:19], v253 offset:0
	ds_read_b128 v[12:15], v253 offset:2048
	ds_read_b128 v[8:11], v253 offset:4096
	ds_read_b128 v[4:7], v253 offset:6144
	v_mfma_f32_16x16x32_bf16 v[188:191], v[176:179], v[156:159], v[212:215]
	v_mfma_f32_16x16x32_bf16 v[192:195], v[168:171], v[156:159], v[242:245]
	v_mfma_f32_16x16x32_bf16 v[188:191], v[172:175], v[160:163], v[188:191]
	v_mfma_f32_16x16x32_bf16 v[192:195], v[164:167], v[160:163], v[192:195]
	v_mfma_f32_16x16x32_bf16 v[196:199], v[176:179], v[148:151], v[180:183]
	v_mfma_f32_16x16x32_bf16 v[200:203], v[168:171], v[148:151], v[184:187]
	v_mfma_f32_16x16x32_bf16 v[196:199], v[172:175], v[152:155], v[196:199]
	v_mfma_f32_16x16x32_bf16 v[200:203], v[164:167], v[152:155], v[200:203]
	s_nop 2
	v_exp_f32_e32 v188, v188
	v_exp_f32_e32 v189, v189
	v_exp_f32_e32 v190, v190
	v_exp_f32_e32 v191, v191
	v_exp_f32_e32 v192, v192
	v_exp_f32_e32 v193, v193
	v_exp_f32_e32 v194, v194
	v_exp_f32_e32 v195, v195
	v_cvt_pk_bf16_f32 v246, v188, v189
	v_cvt_pk_bf16_f32 v247, v190, v191
	v_cvt_pk_bf16_f32 v248, v192, v193
	v_cvt_pk_bf16_f32 v249, v194, v195
	v_add_f32_e32 v188, v188, v189
	v_add_f32_e32 v190, v190, v191
	v_add_f32_e32 v192, v192, v193
	v_add_f32_e32 v194, v194, v195
	v_add_f32_e32 v188, v188, v190
	v_add_f32_e32 v192, v192, v194
	v_add_f32_e32 v188, v188, v192
	v_add_f32_e32 v225, v225, v188
	v_mfma_f32_16x16x32_bf16 v[188:191], v[176:179], v[140:143], v[80:83]
	v_mfma_f32_16x16x32_bf16 v[192:195], v[168:171], v[140:143], v[84:87]
	v_mfma_f32_16x16x32_bf16 v[188:191], v[172:175], v[144:147], v[188:191]
	v_mfma_f32_16x16x32_bf16 v[192:195], v[164:167], v[144:147], v[192:195]
	v_exp_f32_e32 v196, v196
	v_exp_f32_e32 v197, v197
	v_exp_f32_e32 v198, v198
	v_exp_f32_e32 v199, v199
	v_mfma_f32_16x16x32_bf16 v[112:115], v[32:35], v[246:249], v[112:115]
	v_exp_f32_e32 v200, v200
	v_exp_f32_e32 v201, v201
	v_exp_f32_e32 v202, v202
	v_exp_f32_e32 v203, v203
	v_mfma_f32_16x16x32_bf16 v[108:111], v[28:31], v[246:249], v[108:111]
	v_cvt_pk_bf16_f32 v92, v196, v197
	v_cvt_pk_bf16_f32 v93, v198, v199
	v_cvt_pk_bf16_f32 v94, v200, v201
	v_cvt_pk_bf16_f32 v95, v202, v203
	v_mfma_f32_16x16x32_bf16 v[104:107], v[24:27], v[246:249], v[104:107]
	v_add_f32_e32 v196, v196, v197
	v_add_f32_e32 v198, v198, v199
	v_add_f32_e32 v200, v200, v201
	v_add_f32_e32 v202, v202, v203
	v_mfma_f32_16x16x32_bf16 v[100:103], v[20:23], v[246:249], v[100:103]
	v_add_f32_e32 v196, v196, v198
	v_add_f32_e32 v200, v200, v202
	v_add_f32_e32 v196, v196, v200
	v_add_f32_e32 v224, v224, v196
	v_exp_f32_e32 v188, v188
	v_exp_f32_e32 v189, v189
	v_exp_f32_e32 v190, v190
	v_exp_f32_e32 v191, v191
	v_mfma_f32_16x16x32_bf16 v[128:131], v[32:35], v[92:95], v[128:131]
	v_exp_f32_e32 v192, v192
	v_exp_f32_e32 v193, v193
	v_exp_f32_e32 v194, v194
	v_exp_f32_e32 v195, v195
	v_mfma_f32_16x16x32_bf16 v[124:127], v[28:31], v[92:95], v[124:127]
	v_cvt_pk_bf16_f32 v246, v188, v189
	v_cvt_pk_bf16_f32 v247, v190, v191
	v_cvt_pk_bf16_f32 v248, v192, v193
	v_cvt_pk_bf16_f32 v249, v194, v195
	v_mfma_f32_16x16x32_bf16 v[120:123], v[24:27], v[92:95], v[120:123]
	v_add_f32_e32 v188, v188, v189
	v_add_f32_e32 v190, v190, v191
	v_add_f32_e32 v192, v192, v193
	v_add_f32_e32 v194, v194, v195
	v_mfma_f32_16x16x32_bf16 v[116:119], v[20:23], v[92:95], v[116:119]
	v_add_f32_e32 v188, v188, v190
	v_add_f32_e32 v192, v192, v194
	v_add_f32_e32 v188, v188, v192
	v_add_f32_e32 v223, v223, v188
	v_mfma_f32_16x16x32_bf16 v[64:67], v[32:35], v[246:249], v[64:67]
	v_mfma_f32_16x16x32_bf16 v[60:63], v[28:31], v[246:249], v[60:63]
	v_mfma_f32_16x16x32_bf16 v[56:59], v[24:27], v[246:249], v[56:59]
	v_mfma_f32_16x16x32_bf16 v[52:55], v[20:23], v[246:249], v[52:55]
	v_add_u32_e32 v240, 0x100, v240
	s_waitcnt lgkmcnt(0)
	s_waitcnt vmcnt(2)
	s_barrier
	s_add_u32 s20, s92, 3
	s_cmp_ge_u32 s20, s88
	s_cbranch_scc1 .Latt_sk21
	s_add_u32 s20, s20, s93
	s_lshl_b32 s21, s20, 16
	s_add_u32 s21, s21, s61
	s_lshl_b32 s22, s20, 7
	s_add_u32 s22, s22, s62
	s_add_u32 m0, s95, s94
	s_add_u32 s84, s95, s94
	s_add_u32 s84, s84, 0x2000
	buffer_load_dwordx4 v241, s[24:27], s21 offen lds
	s_mov_b32 m0, s84
	s_nop 0
	buffer_load_dwordx4 v255, s[40:43], s22 offen lds

.Latt_cs22:
	v_add_u32_e32 v251, s23, v233
	v_add_u32_e32 v253, s33, v234
	ds_read_b128 v[176:179], v251 offset:0
	ds_read_b128 v[168:171], v251 offset:4096
	ds_read_b128 v[172:175], v251 offset:2048
	ds_read_b128 v[164:167], v251 offset:6144
	ds_read_b128 v[32:35], v253 offset:0
	ds_read_b128 v[28:31], v253 offset:2048
	ds_read_b128 v[24:27], v253 offset:4096
	ds_read_b128 v[20:23], v253 offset:6144
	v_mfma_f32_16x16x32_bf16 v[188:191], v[48:51], v[156:159], v[180:183]
	v_mfma_f32_16x16x32_bf16 v[192:195], v[40:43], v[156:159], v[184:187]
	v_mfma_f32_16x16x32_bf16 v[188:191], v[44:47], v[160:163], v[188:191]
	v_mfma_f32_16x16x32_bf16 v[192:195], v[36:39], v[160:163], v[192:195]
	v_mfma_f32_16x16x32_bf16 v[196:199], v[48:51], v[148:151], v[80:83]
	v_mfma_f32_16x16x32_bf16 v[200:203], v[40:43], v[148:151], v[84:87]
	v_mfma_f32_16x16x32_bf16 v[196:199], v[44:47], v[152:155], v[196:199]
	v_mfma_f32_16x16x32_bf16 v[200:203], v[36:39], v[152:155], v[200:203]
	s_nop 2
	v_exp_f32_e32 v188, v188
	v_exp_f32_e32 v189, v189
	v_exp_f32_e32 v190, v190
	v_exp_f32_e32 v191, v191
	v_exp_f32_e32 v192, v192
	v_exp_f32_e32 v193, v193
	v_exp_f32_e32 v194, v194
	v_exp_f32_e32 v195, v195
	v_cvt_pk_bf16_f32 v246, v188, v189
	v_cvt_pk_bf16_f32 v247, v190, v191
	v_cvt_pk_bf16_f32 v248, v192, v193
	v_cvt_pk_bf16_f32 v249, v194, v195
	v_add_f32_e32 v188, v188, v189
	v_add_f32_e32 v190, v190, v191
	v_add_f32_e32 v192, v192, v193
	v_add_f32_e32 v194, v194, v195
	v_add_f32_e32 v188, v188, v190
	v_add_f32_e32 v192, v192, v194
	v_add_f32_e32 v188, v188, v192
	v_add_f32_e32 v225, v225, v188
	v_exp_f32_e32 v196, v196
	v_exp_f32_e32 v197, v197
	v_exp_f32_e32 v198, v198
	v_exp_f32_e32 v199, v199
	v_mfma_f32_16x16x32_bf16 v[112:115], v[16:19], v[246:249], v[112:115]
	v_exp_f32_e32 v200, v200
	v_exp_f32_e32 v201, v201
	v_exp_f32_e32 v202, v202
	v_exp_f32_e32 v203, v203
	v_mfma_f32_16x16x32_bf16 v[108:111], v[12:15], v[246:249], v[108:111]
	v_cvt_pk_bf16_f32 v92, v196, v197
	v_cvt_pk_bf16_f32 v93, v198, v199
	v_cvt_pk_bf16_f32 v94, v200, v201
	v_cvt_pk_bf16_f32 v95, v202, v203
	v_mfma_f32_16x16x32_bf16 v[104:107], v[8:11], v[246:249], v[104:107]
	v_add_f32_e32 v196, v196, v197
	v_add_f32_e32 v198, v198, v199
	v_add_f32_e32 v200, v200, v201
	v_add_f32_e32 v202, v202, v203
	v_mfma_f32_16x16x32_bf16 v[100:103], v[4:7], v[246:249], v[100:103]
	v_add_f32_e32 v196, v196, v198
	v_add_f32_e32 v200, v200, v202
	v_add_f32_e32 v196, v196, v200
	v_add_f32_e32 v224, v224, v196
	v_mfma_f32_16x16x32_bf16 v[128:131], v[16:19], v[92:95], v[128:131]
	v_mfma_f32_16x16x32_bf16 v[124:127], v[12:15], v[92:95], v[124:127]
	v_mfma_f32_16x16x32_bf16 v[120:123], v[8:11], v[92:95], v[120:123]
	v_mfma_f32_16x16x32_bf16 v[116:119], v[4:7], v[92:95], v[116:119]
	v_add_u32_e32 v240, 0x100, v240
	s_waitcnt lgkmcnt(0)
	s_waitcnt vmcnt(2)
	s_barrier
	s_add_u32 s20, s92, 3
	s_cmp_ge_u32 s20, s88
	s_cbranch_scc1 .Latt_sk23
	s_add_u32 s20, s20, s93
	s_lshl_b32 s21, s20, 16
	s_add_u32 s21, s21, s61
	s_lshl_b32 s22, s20, 7
	s_add_u32 s22, s22, s62
	s_add_u32 m0, s95, s94
	s_add_u32 s84, s95, s94
	s_add_u32 s84, s84, 0x2000
	buffer_load_dwordx4 v241, s[24:27], s21 offen lds
	s_mov_b32 m0, s84
	s_nop 0
	buffer_load_dwordx4 v255, s[40:43], s22 offen lds

.Latt_F0:
	s_waitcnt lgkmcnt(0)
	s_waitcnt vmcnt(2)
	s_barrier
	s_add_u32 s20, s92, 3
	s_cmp_ge_u32 s20, s88
	s_cbranch_scc1 .Latt_sk25
	s_add_u32 s20, s20, s93
	s_lshl_b32 s21, s20, 16
	s_add_u32 s21, s21, s61
	s_lshl_b32 s22, s20, 7
	s_add_u32 s22, s22, s62
	s_add_u32 m0, s95, s94
	s_add_u32 s84, s95, s94
	s_add_u32 s84, s84, 0x2000
	buffer_load_dwordx4 v241, s[24:27], s21 offen lds
	s_mov_b32 m0, s84
	s_nop 0
	buffer_load_dwordx4 v255, s[40:43], s22 offen lds

.Latt_cdone:
	s_nop 7
	s_cmp_eq_u32 s85, 1
	s_cbranch_scc1 .Latt_went
	s_cmp_eq_u32 s76, 8
	s_cbranch_scc0 .Latt_end
	s_waitcnt lgkmcnt(0)
	s_waitcnt vmcnt(2)
	s_barrier
	s_add_u32 s20, s92, 3
	s_cmp_ge_u32 s20, s88
	s_cbranch_scc1 .Latt_sk37
	s_add_u32 s20, s20, s93
	s_lshl_b32 s21, s20, 16
	s_add_u32 s21, s21, s61
	s_lshl_b32 s22, s20, 7
	s_add_u32 s22, s22, s62
	s_add_u32 m0, s95, s94
	s_add_u32 s84, s95, s94
	s_add_u32 s84, s84, 0x2000
	buffer_load_dwordx4 v241, s[24:27], s21 offen lds
	s_mov_b32 m0, s84
	s_nop 0
	buffer_load_dwordx4 v255, s[40:43], s22 offen lds
